# C item gate loads as 16-byte loads (lower half-wave chunk 2j, upper half chunk 2j+1) plus permlane32_swap in the epilogue: 9 instead of 16 row-per-lane loads
# speedup vs baseline: 1.0121x; 1.0038x over previous
.LBB0_779:
	v_mov_b32_e32 v43, v0
	s_ashr_i32 s5, s3, 31
	v_ashrrev_i32_e32 v44, 7, v43
	s_waitcnt vmcnt(2)
	v_add_u32_e32 v164, s2, v44
	v_ashrrev_i32_e32 v165, 31, v164
	v_and_b32_e32 v168, 31, v43
	s_waitcnt vmcnt(0)
	v_lshlrev_b64 v[2:3], 15, v[164:165]
	v_bfe_u32 v169, v43, 5, 1
	v_lshl_add_u64 v[2:3], s[56:57], 0, v[2:3]
	v_lshlrev_b32_e32 v154, 8, v168
	v_lshl_add_u64 v[2:3], v[2:3], 0, v[154:155]
	v_lshlrev_b32_e32 v154, 4, v169
	v_lshl_add_u64 v[18:19], v[2:3], 0, v[154:155]
	v_add_co_u32_e32 v20, vcc, s14, v18
	v_ashrrev_i32_e32 v45, 2, v43
	s_nop 0
	v_addc_co_u32_e32 v21, vcc, 0, v19, vcc
	v_add_co_u32_e32 v22, vcc, s17, v18
	global_load_dwordx4 v[2:5], v[18:19], off
	global_load_dwordx4 v[6:9], v[20:21], off
	v_addc_co_u32_e32 v23, vcc, 0, v19, vcc
	v_add_co_u32_e32 v24, vcc, s30, v18
	global_load_dwordx4 v[10:13], v[22:23], off
	s_nop 0
	v_addc_co_u32_e32 v25, vcc, 0, v19, vcc
	global_load_dwordx4 v[14:17], v[24:25], off
	global_load_dwordx4 v[138:141], v[18:19], off offset:32
	global_load_dwordx4 v[142:145], v[20:21], off offset:32
	global_load_dwordx4 v[146:149], v[22:23], off offset:32
	global_load_dwordx4 v[150:153], v[24:25], off offset:32
	global_load_dwordx4 v[126:129], v[20:21], off offset:64
	global_load_dwordx4 v[130:133], v[22:23], off offset:64
	global_load_dwordx4 v[134:137], v[24:25], off offset:64
	global_load_dwordx4 v[114:117], v[20:21], off offset:96
	global_load_dwordx4 v[118:121], v[22:23], off offset:96
	global_load_dwordx4 v[122:125], v[24:25], off offset:96
	global_load_dwordx4 v[106:109], v[22:23], off offset:128
	global_load_dwordx4 v[110:113], v[24:25], off offset:128
	global_load_dwordx4 v[98:101], v[22:23], off offset:160
	global_load_dwordx4 v[102:105], v[24:25], off offset:160
	global_load_dwordx4 v[94:97], v[24:25], off offset:192
	global_load_dwordx4 v[90:93], v[24:25], off offset:224
	v_add_u32_e32 v18, s3, v45
	v_ashrrev_i32_e32 v19, 31, v18
	v_lshlrev_b32_e32 v20, 6, v43
	v_lshlrev_b64 v[18:19], 12, v[18:19]
	v_and_b32_e32 v46, 0xc0, v20
	v_lshl_add_u64 v[18:19], s[60:61], 0, v[18:19]
	v_lshlrev_b32_e32 v20, 1, v46
	v_mov_b32_e32 v21, v155
	v_lshl_add_u64 v[34:35], v[18:19], 0, v[20:21]
	global_load_dwordx4 v[18:21], v[34:35], off offset:3632
	global_load_dwordx4 v[22:25], v[34:35], off offset:3616
	global_load_dwordx4 v[26:29], v[34:35], off offset:3600
	global_load_dwordx4 v[30:33], v[34:35], off offset:3584
	global_load_dwordx4 v[36:39], v[34:35], off offset:3680
	global_load_dwordx4 v[202:205], v[34:35], off offset:3664
	global_load_dwordx4 v[48:51], v[34:35], off offset:3648
	global_load_dwordx4 v[206:209], v[34:35], off offset:3696
	v_and_b32_e32 v215, 31, v0
	v_add_u32_e32 v215, s3, v215
	v_lshlrev_b32_e32 v215, 12, v215
	v_and_b32_e32 v245, 0x1c0, v0
	v_add_u32_e32 v215, v215, v245
	v_bfe_u32 v245, v0, 5, 1
	v_lshl_add_u32 v245, v245, 3, v215
	v_bfe_u32 v215, v0, 5, 1
	v_lshl_add_u32 v215, v215, 3, v245
	global_load_dwordx4 v[216:219], v215, s[60:61] offset:3072
	global_load_dwordx4 v[220:223], v215, s[60:61] offset:3104
	s_add_u32 s98, s60, 0x20000
	s_addc_u32 s99, s61, 0
	global_load_dwordx4 v[224:227], v215, s[98:99] offset:3072
	global_load_dwordx4 v[228:231], v215, s[98:99] offset:3104
	s_add_u32 s100, s60, 0x40000
	s_addc_u32 s101, s61, 0
	global_load_dwordx4 v[232:235], v215, s[100:101] offset:3072
	global_load_dwordx4 v[236:239], v215, s[100:101] offset:3104
	s_add_u32 s98, s60, 0x60000
	s_addc_u32 s99, s61, 0
	global_load_dwordx4 v[252:255], v215, s[98:99] offset:3072
	global_load_dwordx2 v[240:241], v245, s[98:99] offset:3104
	global_load_dwordx2 v[246:247], v245, s[98:99] offset:3120
	v_lshrrev_b32_e32 v42, 5, v43
	s_add_i32 s4, s4, s46
	s_waitcnt vmcnt(16)
	v_lshlrev_b32_e32 v178, 16, v18
	s_waitcnt vmcnt(15)
	v_lshlrev_b32_e32 v186, 16, v22
	s_waitcnt vmcnt(14)
	v_lshlrev_b32_e32 v194, 16, v26
	s_waitcnt vmcnt(13)
	v_lshlrev_b32_e32 v200, 16, v30
	v_and_b32_e32 v199, 0xffff0000, v30
	v_add_f32_e32 v30, 0, v200
	v_lshlrev_b32_e32 v198, 16, v31
	v_add_f32_e32 v30, v30, v199
	v_and_b32_e32 v197, 0xffff0000, v31
	v_mul_f32_e32 v31, v199, v199
	v_add_f32_e32 v30, v30, v198
	v_lshlrev_b32_e32 v196, 16, v32
	v_fmac_f32_e32 v31, v200, v200
	v_add_f32_e32 v30, v30, v197
	v_and_b32_e32 v195, 0xffff0000, v32
	v_fmac_f32_e32 v31, v198, v198
	v_add_f32_e32 v30, v30, v196
	v_lshlrev_b32_e32 v193, 16, v33
	v_fmac_f32_e32 v31, v197, v197
	v_add_f32_e32 v30, v30, v195
	v_and_b32_e32 v191, 0xffff0000, v33
	v_fmac_f32_e32 v31, v196, v196
	v_add_f32_e32 v30, v30, v193
	v_fmac_f32_e32 v31, v195, v195
	v_add_f32_e32 v30, v30, v191
	v_fmac_f32_e32 v31, v193, v193
	v_and_b32_e32 v192, 0xffff0000, v26
	v_add_f32_e32 v26, v30, v194
	v_fmac_f32_e32 v31, v191, v191
	v_lshlrev_b32_e32 v190, 16, v27
	v_add_f32_e32 v26, v26, v192
	v_and_b32_e32 v189, 0xffff0000, v27
	v_fmac_f32_e32 v31, v194, v194
	v_add_f32_e32 v26, v26, v190
	v_lshlrev_b32_e32 v188, 16, v28
	v_fmac_f32_e32 v31, v192, v192
	v_add_f32_e32 v26, v26, v189
	v_and_b32_e32 v187, 0xffff0000, v28
	v_fmac_f32_e32 v31, v190, v190
	v_add_f32_e32 v26, v26, v188
	v_lshlrev_b32_e32 v184, 16, v29
	v_fmac_f32_e32 v31, v189, v189
	v_add_f32_e32 v26, v26, v187
	v_and_b32_e32 v182, 0xffff0000, v29
	v_fmac_f32_e32 v31, v188, v188
	v_add_f32_e32 v26, v26, v184
	v_fmac_f32_e32 v31, v187, v187
	v_add_f32_e32 v26, v26, v182
	v_fmac_f32_e32 v31, v184, v184
	v_and_b32_e32 v185, 0xffff0000, v22
	v_add_f32_e32 v22, v26, v186
	v_fmac_f32_e32 v31, v182, v182
	v_lshlrev_b32_e32 v183, 16, v23
	v_add_f32_e32 v22, v22, v185
	v_and_b32_e32 v179, 0xffff0000, v23
	v_fmac_f32_e32 v31, v186, v186
	v_add_f32_e32 v22, v22, v183
	v_lshlrev_b32_e32 v177, 16, v24
	v_fmac_f32_e32 v31, v185, v185
	v_add_f32_e32 v22, v22, v179
	v_and_b32_e32 v175, 0xffff0000, v24
	v_fmac_f32_e32 v31, v183, v183
	v_add_f32_e32 v22, v22, v177
	v_lshlrev_b32_e32 v173, 16, v25
	v_fmac_f32_e32 v31, v179, v179
	v_add_f32_e32 v22, v22, v175
	v_and_b32_e32 v171, 0xffff0000, v25
	v_fmac_f32_e32 v31, v177, v177
	v_add_f32_e32 v22, v22, v173
	v_fmac_f32_e32 v31, v175, v175
	v_add_f32_e32 v22, v22, v171
	v_fmac_f32_e32 v31, v173, v173
	v_and_b32_e32 v176, 0xffff0000, v18
	v_add_f32_e32 v18, v22, v178
	v_fmac_f32_e32 v31, v171, v171
	v_lshlrev_b32_e32 v174, 16, v19
	v_add_f32_e32 v18, v18, v176
	v_and_b32_e32 v172, 0xffff0000, v19
	v_fmac_f32_e32 v31, v178, v178
	v_add_f32_e32 v18, v18, v174
	v_lshlrev_b32_e32 v167, 16, v20
	v_fmac_f32_e32 v31, v176, v176
	v_add_f32_e32 v18, v18, v172
	v_and_b32_e32 v165, 0xffff0000, v20
	v_fmac_f32_e32 v31, v174, v174
	v_add_f32_e32 v18, v18, v167
	v_lshlrev_b32_e32 v64, 16, v21
	v_fmac_f32_e32 v31, v172, v172
	v_add_f32_e32 v18, v18, v165
	v_and_b32_e32 v62, 0xffff0000, v21
	v_fmac_f32_e32 v31, v167, v167
	v_add_f32_e32 v18, v18, v64
	v_fmac_f32_e32 v31, v165, v165
	v_add_f32_e32 v18, v18, v62
	s_waitcnt vmcnt(10)
	v_lshlrev_b32_e32 v170, 16, v48
	v_fmac_f32_e32 v31, v64, v64
	v_and_b32_e32 v166, 0xffff0000, v48
	v_add_f32_e32 v18, v18, v170
	v_fmac_f32_e32 v31, v62, v62
	v_lshlrev_b32_e32 v65, 16, v49
	v_add_f32_e32 v18, v18, v166
	v_and_b32_e32 v63, 0xffff0000, v49
	v_fmac_f32_e32 v31, v170, v170
	v_add_f32_e32 v18, v18, v65
	v_lshlrev_b32_e32 v60, 16, v50
	v_fmac_f32_e32 v31, v166, v166
	v_add_f32_e32 v18, v18, v63
	v_and_b32_e32 v59, 0xffff0000, v50
	v_fmac_f32_e32 v31, v65, v65
	v_add_f32_e32 v18, v18, v60
	v_lshlrev_b32_e32 v57, 16, v51
	v_fmac_f32_e32 v31, v63, v63
	v_add_f32_e32 v18, v18, v59
	v_and_b32_e32 v55, 0xffff0000, v51
	v_fmac_f32_e32 v31, v60, v60
	v_add_f32_e32 v18, v18, v57
	v_fmac_f32_e32 v31, v59, v59
	v_add_f32_e32 v18, v18, v55
	v_lshlrev_b32_e32 v61, 16, v202
	v_fmac_f32_e32 v31, v57, v57
	v_and_b32_e32 v58, 0xffff0000, v202
	v_add_f32_e32 v18, v18, v61
	v_fmac_f32_e32 v31, v55, v55
	v_lshlrev_b32_e32 v56, 16, v203
	v_add_f32_e32 v18, v18, v58
	v_and_b32_e32 v54, 0xffff0000, v203
	v_fmac_f32_e32 v31, v61, v61
	v_add_f32_e32 v18, v18, v56
	v_lshlrev_b32_e32 v53, 16, v204
	v_fmac_f32_e32 v31, v58, v58
	v_add_f32_e32 v18, v18, v54
	v_and_b32_e32 v51, 0xffff0000, v204
	v_fmac_f32_e32 v31, v56, v56
	v_add_f32_e32 v18, v18, v53
	v_lshlrev_b32_e32 v49, 16, v205
	v_fmac_f32_e32 v31, v54, v54
	v_add_f32_e32 v18, v18, v51
	v_and_b32_e32 v47, 0xffff0000, v205
	v_fmac_f32_e32 v31, v53, v53
	v_add_f32_e32 v18, v18, v49
	v_fmac_f32_e32 v31, v51, v51
	v_add_f32_e32 v18, v18, v47
	v_lshlrev_b32_e32 v52, 16, v36
	v_fmac_f32_e32 v31, v49, v49
	v_and_b32_e32 v50, 0xffff0000, v36
	v_add_f32_e32 v18, v18, v52
	v_fmac_f32_e32 v31, v47, v47
	v_lshlrev_b32_e32 v48, 16, v37
	v_add_f32_e32 v18, v18, v50
	v_fmac_f32_e32 v31, v52, v52
	v_add_f32_e32 v18, v18, v48
	v_and_b32_e32 v37, 0xffff0000, v37
	v_fmac_f32_e32 v31, v50, v50
	v_lshlrev_b32_e32 v34, 16, v38
	v_mov_b32_e32 v35, v37
	v_add_f32_e32 v20, v18, v37
	v_fmac_f32_e32 v31, v48, v48
	v_and_b32_e32 v24, 0xffff0000, v38
	v_pk_mul_f32 v[18:19], v[34:35], v[34:35]
	v_add_f32_e32 v20, v20, v34
	v_lshlrev_b32_e32 v25, 16, v39
	v_add_f32_e32 v19, v19, v31
	v_add_f32_e32 v20, v20, v24
	v_add_f32_e32 v21, v18, v19
	v_pk_mul_f32 v[18:19], v[24:25], v[24:25]
	v_add_f32_e32 v20, v20, v25
	v_and_b32_e32 v33, 0xffff0000, v39
	v_add_f32_e32 v18, v18, v21
	s_waitcnt vmcnt(9)
	v_lshlrev_b32_e32 v28, 16, v206
	v_mov_b32_e32 v29, v33
	v_add_f32_e32 v20, v20, v33
	v_add_f32_e32 v21, v19, v18
	v_and_b32_e32 v22, 0xffff0000, v206
	v_pk_mul_f32 v[18:19], v[28:29], v[28:29]
	v_add_f32_e32 v20, v20, v28
	v_lshlrev_b32_e32 v23, 16, v207
	v_add_f32_e32 v19, v19, v21
	v_add_f32_e32 v20, v20, v22
	v_add_f32_e32 v21, v18, v19
	v_pk_mul_f32 v[18:19], v[22:23], v[22:23]
	v_add_f32_e32 v29, v20, v23
	v_and_b32_e32 v31, 0xffff0000, v207
	v_add_f32_e32 v18, v18, v21
	v_lshlrev_b32_e32 v26, 16, v208
	v_mov_b32_e32 v27, v31
	v_add_f32_e32 v29, v29, v31
	v_and_b32_e32 v36, s0, v38
	v_add_f32_e32 v18, v19, v18
	v_and_b32_e32 v20, 0xffff0000, v208
	v_pk_mul_f32 v[38:39], v[26:27], v[26:27]
	v_add_f32_e32 v27, v29, v26
	v_lshlrev_b32_e32 v21, 16, v209
	v_add_f32_e32 v18, v39, v18
	v_add_f32_e32 v27, v27, v20
	v_and_b32_e32 v29, 64, v181
	v_add_f32_e32 v18, v38, v18
	v_pk_mul_f32 v[40:41], v[20:21], v[20:21]
	v_add_f32_e32 v39, v27, v21
	v_xor_b32_e32 v27, 1, v181
	v_add_u32_e32 v29, 64, v29
	v_and_b32_e32 v19, 0xffff0000, v209
	v_add_f32_e32 v18, v40, v18
	v_cmp_lt_i32_e32 vcc, v27, v29
	v_add_f32_e32 v18, v41, v18
	v_mul_f32_e32 v38, v19, v19
	v_cndmask_b32_e32 v27, v181, v27, vcc
	v_lshlrev_b32_e32 v27, 2, v27
	v_pk_add_f32 v[38:39], v[38:39], v[18:19]
	ds_bpermute_b32 v41, v27, v39
	ds_bpermute_b32 v40, v27, v38
	v_xor_b32_e32 v35, 2, v181
	v_cmp_lt_i32_e32 vcc, v35, v29
	v_and_b32_e32 v30, s0, v206
	v_mov_b32_e32 v32, v36
	v_cndmask_b32_e32 v29, v181, v35, vcc
	v_lshlrev_b32_e32 v29, 2, v29
	s_waitcnt lgkmcnt(0)
	v_pk_add_f32 v[38:39], v[38:39], v[40:41]
	ds_bpermute_b32 v41, v29, v39
	ds_bpermute_b32 v40, v29, v38
	s_waitcnt lgkmcnt(0)
	v_pk_add_f32 v[40:41], v[38:39], v[40:41]
	s_nop 0
	v_pk_mul_f32 v[38:39], v[40:41], s[22:23] op_sel_hi:[1,0]
	v_pk_fma_f32 v[36:37], v[40:41], s[22:23], v[36:37] op_sel_hi:[1,0,1] neg_lo:[1,0,0] neg_hi:[1,0,0]
	v_fma_f32 v18, -v39, v39, v38
	v_max_f32_e32 v18, 0, v18
	v_add_f32_e32 v18, 0x358637bd, v18
	v_cmp_gt_f32_e32 vcc, s33, v18
	v_mul_f32_e32 v27, 0x4b800000, v18
	v_sub_f32_e32 v29, v200, v39
	v_cndmask_b32_e32 v18, v18, v27, vcc
	v_rsq_f32_e32 v18, v18
	v_sub_f32_e32 v19, v19, v39
	v_mul_f32_e32 v27, 0x45800000, v18
	v_cndmask_b32_e32 v18, v18, v27, vcc
	v_mul_f32_e32 v29, v29, v18
	v_lshlrev_b32_e32 v27, 1, v45
	v_bfe_u32 v35, v29, 16, 1
	v_ashrrev_i32_e32 v45, 1, v43
	v_and_b32_e32 v27, 14, v27
	v_add3_u32 v29, v29, v35, s15
	v_lshl_add_u32 v35, v46, 8, 32
	v_and_b32_e32 v46, -16, v45
	v_add3_u32 v200, v35, v46, v27
	ds_write_b16_d16_hi v200, v29 offset:55296
	v_mul_f32_e64 v215, -v39, v18
	v_fma_f32 v29, v199, v18, v215
	v_cvt_pk_bf16_f32 v29, v29, v29
	v_bitop3_b32 v199, v45, 16, -16 bitop3:0x6c
	v_add3_u32 v201, v35, v199, v27
	ds_write_b16 v201, v29 offset:55552
	v_fma_f32 v29, v198, v18, v215
	v_cvt_pk_bf16_f32 v29, v29, v29
	v_bitop3_b32 v198, v45, 32, -16 bitop3:0x6c
	v_add3_u32 v202, v35, v198, v27
	ds_write_b16 v202, v29 offset:55808
	v_fma_f32 v29, v197, v18, v215
	v_cvt_pk_bf16_f32 v29, v29, v29
	v_bitop3_b32 v197, v45, 48, -16 bitop3:0x6c
	v_add3_u32 v203, v35, v197, v27
	ds_write_b16 v203, v29 offset:56064
	v_fma_f32 v29, v196, v18, v215
	v_cvt_pk_bf16_f32 v29, v29, v29
	v_bitop3_b32 v196, v45, 64, -16 bitop3:0x6c
	v_add3_u32 v204, v35, v196, v27
	ds_write_b16 v204, v29 offset:56320
	v_fma_f32 v29, v195, v18, v215
	v_cvt_pk_bf16_f32 v29, v29, v29
	v_bitop3_b32 v195, v45, s34, -16 bitop3:0x6c
	v_add3_u32 v205, v35, v195, v27
	ds_write_b16 v205, v29 offset:56576
	v_fma_f32 v29, v193, v18, v215
	v_cvt_pk_bf16_f32 v29, v29, v29
	v_bitop3_b32 v193, v45, s31, -16 bitop3:0x6c
	v_add3_u32 v206, v35, v193, v27
	ds_write_b16 v206, v29 offset:56832
	v_fma_f32 v29, v191, v18, v215
	v_cvt_pk_bf16_f32 v29, v29, v29
	v_bitop3_b32 v191, v45, s13, -16 bitop3:0x6c
	v_add3_u32 v207, v35, v191, v27
	ds_write_b16 v207, v29 offset:57088
	v_fma_f32 v29, v194, v18, v215
	v_cvt_pk_bf16_f32 v29, v29, v29
	v_bitop3_b32 v194, v45, s12, -16 bitop3:0x6c
	v_add3_u32 v208, v35, v194, v27
	ds_write_b16 v208, v29 offset:57344
	v_fma_f32 v29, v192, v18, v215
	v_cvt_pk_bf16_f32 v29, v29, v29
	v_bitop3_b32 v192, v45, s35, -16 bitop3:0x6c
	v_add3_u32 v209, v35, v192, v27
	ds_write_b16 v209, v29 offset:57600
	v_fma_f32 v29, v190, v18, v215
	v_cvt_pk_bf16_f32 v29, v29, v29
	v_bitop3_b32 v190, v45, s36, -16 bitop3:0x6c
	v_add3_u32 v210, v35, v190, v27
	ds_write_b16 v210, v29 offset:57856
	v_fma_f32 v29, v189, v18, v215
	v_cvt_pk_bf16_f32 v29, v29, v29
	v_bitop3_b32 v189, v45, s37, -16 bitop3:0x6c
	v_add3_u32 v211, v35, v189, v27
	ds_write_b16 v211, v29 offset:58112
	v_fma_f32 v29, v188, v18, v215
	v_cvt_pk_bf16_f32 v29, v29, v29
	v_bitop3_b32 v188, v45, s16, -16 bitop3:0x6c
	v_add3_u32 v212, v35, v188, v27
	ds_write_b16 v212, v29 offset:58368
	v_fma_f32 v29, v187, v18, v215
	v_cvt_pk_bf16_f32 v29, v29, v29
	v_bitop3_b32 v187, v45, s42, -16 bitop3:0x6c
	v_add3_u32 v213, v35, v187, v27
	ds_write_b16 v213, v29 offset:58624
	v_fma_f32 v29, v184, v18, v215
	v_cvt_pk_bf16_f32 v29, v29, v29
	v_bitop3_b32 v184, v45, s43, -16 bitop3:0x6c
	v_add3_u32 v214, v35, v184, v27
	ds_write_b16 v214, v29 offset:58880
	v_sub_f32_e32 v29, v182, v39
	v_mul_f32_e32 v29, v29, v18
	v_bfe_u32 v182, v29, 16, 1
	v_bitop3_b32 v45, v45, s94, -16 bitop3:0x6c
	v_add_u32_e32 v38, 0xd800, v35
	v_add3_u32 v29, v29, v182, s15
	v_add3_u32 v35, v35, v45, v27
	ds_write_b16_d16_hi v35, v29 offset:59136
	v_fma_f32 v29, v186, v18, v215
	v_cvt_pk_bf16_f32 v29, v29, v29
	ds_write_b16 v200, v29 offset:59392
	v_fma_f32 v29, v185, v18, v215
	v_cvt_pk_bf16_f32 v29, v29, v29
	ds_write_b16 v201, v29 offset:59648
	v_fma_f32 v29, v183, v18, v215
	v_cvt_pk_bf16_f32 v29, v29, v29
	ds_write_b16 v202, v29 offset:59904
	v_fma_f32 v29, v179, v18, v215
	v_cvt_pk_bf16_f32 v29, v29, v29
	ds_write_b16 v203, v29 offset:60160
	v_fma_f32 v29, v177, v18, v215
	v_cvt_pk_bf16_f32 v29, v29, v29
	ds_write_b16 v204, v29 offset:60416
	v_fma_f32 v29, v175, v18, v215
	v_cvt_pk_bf16_f32 v29, v29, v29
	ds_write_b16 v205, v29 offset:60672
	v_fma_f32 v29, v173, v18, v215
	v_cvt_pk_bf16_f32 v29, v29, v29
	ds_write_b16 v206, v29 offset:60928
	v_fma_f32 v29, v171, v18, v215
	v_cvt_pk_bf16_f32 v29, v29, v29
	ds_write_b16 v207, v29 offset:61184
	v_fma_f32 v29, v178, v18, v215
	v_cvt_pk_bf16_f32 v29, v29, v29
	ds_write_b16 v208, v29 offset:61440
	v_fma_f32 v29, v176, v18, v215
	v_cvt_pk_bf16_f32 v29, v29, v29
	ds_write_b16 v209, v29 offset:61696
	v_fma_f32 v29, v174, v18, v215
	v_cvt_pk_bf16_f32 v29, v29, v29
	ds_write_b16 v210, v29 offset:61952
	v_fma_f32 v29, v172, v18, v215
	v_cvt_pk_bf16_f32 v29, v29, v29
	ds_write_b16 v211, v29 offset:62208
	v_fma_f32 v29, v167, v18, v215
	v_cvt_pk_bf16_f32 v29, v29, v29
	ds_write_b16 v212, v29 offset:62464
	v_fma_f32 v29, v165, v18, v215
	v_cvt_pk_bf16_f32 v29, v29, v29
	ds_write_b16 v213, v29 offset:62720
	v_fma_f32 v29, v64, v18, v215
	v_cvt_pk_bf16_f32 v29, v29, v29
	ds_write_b16 v214, v29 offset:62976
	v_fma_f32 v29, v62, v18, v215
	v_cvt_pk_bf16_f32 v29, v29, v29
	ds_write_b16 v35, v29 offset:63232
	v_fma_f32 v29, v170, v18, v215
	v_cvt_pk_bf16_f32 v29, v29, v29
	ds_write_b16 v200, v29 offset:63488
	v_fma_f32 v29, v166, v18, v215
	v_cvt_pk_bf16_f32 v29, v29, v29
	ds_write_b16 v201, v29 offset:63744
	v_fma_f32 v29, v65, v18, v215
	v_cvt_pk_bf16_f32 v29, v29, v29
	ds_write_b16 v202, v29 offset:64000
	v_fma_f32 v29, v63, v18, v215
	v_cvt_pk_bf16_f32 v29, v29, v29
	ds_write_b16 v203, v29 offset:64256
	v_fma_f32 v29, v60, v18, v215
	v_cvt_pk_bf16_f32 v29, v29, v29
	ds_write_b16 v204, v29 offset:64512
	v_fma_f32 v29, v59, v18, v215
	v_cvt_pk_bf16_f32 v29, v29, v29
	ds_write_b16 v205, v29 offset:64768
	v_fma_f32 v29, v57, v18, v215
	v_cvt_pk_bf16_f32 v29, v29, v29
	ds_write_b16 v206, v29 offset:65024
	v_fma_f32 v29, v55, v18, v215
	v_cvt_pk_bf16_f32 v29, v29, v29
	ds_write_b16 v207, v29 offset:65280
	v_fma_f32 v29, v61, v18, v215
	v_cvt_pk_bf16_f32 v29, v29, v29
	v_add3_u32 v35, v38, v194, v27
	ds_write_b16 v35, v29 offset:10240
	v_fma_f32 v29, v58, v18, v215
	v_cvt_pk_bf16_f32 v29, v29, v29
	v_add3_u32 v55, v38, v192, v27
	ds_write_b16 v55, v29 offset:10496
	v_fma_f32 v29, v56, v18, v215
	v_cvt_pk_bf16_f32 v29, v29, v29
	v_add3_u32 v56, v38, v190, v27
	ds_write_b16 v56, v29 offset:10752
	v_fma_f32 v29, v54, v18, v215
	v_cvt_pk_bf16_f32 v29, v29, v29
	v_add3_u32 v54, v38, v189, v27
	ds_write_b16 v54, v29 offset:11008
	v_fma_f32 v29, v53, v18, v215
	v_cvt_pk_bf16_f32 v29, v29, v29
	v_add3_u32 v53, v38, v188, v27
	ds_write_b16 v53, v29 offset:11264
	v_fma_f32 v29, v51, v18, v215
	v_cvt_pk_bf16_f32 v29, v29, v29
	v_add3_u32 v51, v38, v187, v27
	ds_write_b16 v51, v29 offset:11520
	v_fma_f32 v29, v49, v18, v215
	v_cvt_pk_bf16_f32 v29, v29, v29
	v_add3_u32 v49, v38, v184, v27
	ds_write_b16 v49, v29 offset:11776
	v_fma_f32 v29, v47, v18, v215
	v_cvt_pk_bf16_f32 v29, v29, v29
	v_add3_u32 v45, v38, v45, v27
	ds_write_b16 v45, v29 offset:12032
	v_fma_f32 v29, v52, v18, v215
	v_cvt_pk_bf16_f32 v29, v29, v29
	v_add3_u32 v46, v38, v46, v27
	ds_write_b16 v46, v29 offset:12288
	v_fma_f32 v29, v50, v18, v215
	v_cvt_pk_bf16_f32 v29, v29, v29
	v_add3_u32 v46, v38, v199, v27
	ds_write_b16 v46, v29 offset:12544
	v_fma_f32 v29, v48, v18, v215
	v_cvt_pk_bf16_f32 v29, v29, v29
	v_add3_u32 v46, v38, v198, v27
	ds_write_b16 v46, v29 offset:12800
	v_mul_f32_e32 v29, v37, v18
	v_bfe_u32 v36, v29, 16, 1
	v_add3_u32 v29, v29, v36, s15
	v_add3_u32 v36, v38, v197, v27
	ds_write_b16_d16_hi v36, v29 offset:13056
	v_fma_f32 v29, v34, v18, v215
	v_cvt_pk_bf16_f32 v29, v29, v29
	v_add3_u32 v34, v38, v196, v27
	ds_write_b16 v34, v29 offset:13312
	v_sub_f32_e32 v29, v24, v39
	v_pk_fma_f32 v[24:25], v[40:41], s[22:23], v[24:25] op_sel_hi:[1,0,1] neg_lo:[1,0,0] neg_hi:[1,0,0]
	v_mul_f32_e32 v29, v29, v18
	v_mul_f32_e32 v24, v25, v18
	v_bfe_u32 v34, v29, 16, 1
	v_bfe_u32 v25, v24, 16, 1
	v_add3_u32 v29, v29, v34, s15
	v_add3_u32 v34, v38, v195, v27
	v_add3_u32 v24, v24, v25, s15
	v_add3_u32 v25, v38, v193, v27
	ds_write_b16_d16_hi v34, v29 offset:13568
	ds_write_b16_d16_hi v25, v24 offset:13824
	v_pk_fma_f32 v[24:25], v[40:41], s[22:23], v[32:33] op_sel_hi:[1,0,1] neg_lo:[1,0,0] neg_hi:[1,0,0]
	v_and_b32_e32 v167, 15, v43
	v_mul_f32_e32 v24, v25, v18
	v_bfe_u32 v25, v24, 16, 1
	v_add3_u32 v24, v24, v25, s15
	v_add3_u32 v25, v38, v191, v27
	ds_write_b16_d16_hi v25, v24 offset:14080
	v_fma_f32 v24, v28, v18, v215
	v_cvt_pk_bf16_f32 v24, v24, v24
	ds_write_b16 v35, v24 offset:14336
	v_sub_f32_e32 v24, v22, v39
	v_pk_fma_f32 v[22:23], v[40:41], s[22:23], v[22:23] op_sel_hi:[1,0,1] neg_lo:[1,0,0] neg_hi:[1,0,0]
	v_mul_f32_e32 v24, v24, v18
	v_mul_f32_e32 v22, v23, v18
	v_bfe_u32 v25, v24, 16, 1
	v_bfe_u32 v23, v22, 16, 1
	v_add3_u32 v24, v24, v25, s15
	v_add3_u32 v22, v22, v23, s15
	ds_write_b16_d16_hi v55, v24 offset:14592
	ds_write_b16_d16_hi v56, v22 offset:14848
	v_pk_fma_f32 v[22:23], v[40:41], s[22:23], v[30:31] op_sel_hi:[1,0,1] neg_lo:[1,0,0] neg_hi:[1,0,0]
	s_nop 0
	v_mul_f32_e32 v22, v23, v18
	v_bfe_u32 v23, v22, 16, 1
	v_add3_u32 v22, v22, v23, s15
	ds_write_b16_d16_hi v54, v22 offset:15104
	v_fma_f32 v22, v26, v18, v215
	v_cvt_pk_bf16_f32 v22, v22, v22
	ds_write_b16 v53, v22 offset:15360
	v_sub_f32_e32 v22, v20, v39
	v_pk_fma_f32 v[20:21], v[40:41], s[22:23], v[20:21] op_sel_hi:[1,0,1] neg_lo:[1,0,0] neg_hi:[1,0,0]
	v_mul_f32_e32 v22, v22, v18
	v_mul_f32_e32 v20, v21, v18
	v_mul_f32_e32 v18, v19, v18
	v_bfe_u32 v23, v22, 16, 1
	v_bfe_u32 v21, v20, 16, 1
	v_bfe_u32 v19, v18, 16, 1
	v_add3_u32 v22, v22, v23, s15
	v_add3_u32 v20, v20, v21, s15
	v_add3_u32 v18, v18, v19, s15
	ds_write_b16_d16_hi v51, v22 offset:15616
	ds_write_b16_d16_hi v49, v20 offset:15872
	ds_write_b16_d16_hi v45, v18 offset:16128
	v_lshrrev_b32_e32 v18, 1, v43
	v_and_b32_e32 v18, 32, v18
	v_lshl_or_b32 v166, v44, 6, v18
	v_or_b32_e32 v18, v166, v168
	v_lshl_add_u32 v165, v18, 8, 32
	v_bitop3_b32 v18, v42, v167, 1 bitop3:0x6c
	v_lshl_add_u32 v18, v18, 4, v165
	s_waitcnt lgkmcnt(0)
	s_barrier
	ds_read_b128 v[170:173], v18 offset:55296
	s_waitcnt lgkmcnt(0)
	v_mfma_f32_32x32x16_bf16 v[50:65], v[170:173], v[2:5], 0
	v_mfma_f32_32x32x16_bf16 v[34:49], v[170:173], v[6:9], 0
	v_mfma_f32_32x32x16_bf16 v[18:33], v[170:173], v[10:13], 0
	v_mfma_f32_32x32x16_bf16 v[2:17], v[170:173], v[14:17], 0
	v_bitop3_b32 v170, v169, v167, 2 bitop3:0x36
	v_lshl_add_u32 v170, v170, 4, v165
	ds_read_b128 v[170:173], v170 offset:55296
	s_waitcnt lgkmcnt(0)
	v_mfma_f32_32x32x16_bf16 v[50:65], v[170:173], v[138:141], v[50:65]
	v_bitop3_b32 v138, v169, v167, 4 bitop3:0x36
	v_lshl_add_u32 v138, v138, 4, v165
	ds_read_b128 v[138:141], v138 offset:55296
	v_mfma_f32_32x32x16_bf16 v[34:49], v[170:173], v[142:145], v[34:49]
	v_mfma_f32_32x32x16_bf16 v[18:33], v[170:173], v[146:149], v[18:33]
	s_waitcnt lgkmcnt(0)
	v_mfma_f32_32x32x16_bf16 v[34:49], v[138:141], v[126:129], v[34:49]
	v_bitop3_b32 v126, v169, v167, 6 bitop3:0x36
	v_lshl_add_u32 v126, v126, 4, v165
	ds_read_b128 v[126:129], v126 offset:55296
	v_mfma_f32_32x32x16_bf16 v[2:17], v[170:173], v[150:153], v[2:17]
	v_mfma_f32_32x32x16_bf16 v[18:33], v[138:141], v[130:133], v[18:33]
	s_waitcnt lgkmcnt(0)
	v_mfma_f32_32x32x16_bf16 v[34:49], v[126:129], v[114:117], v[34:49]
	v_bitop3_b32 v114, v169, v167, 8 bitop3:0x36
	v_lshl_add_u32 v114, v114, 4, v165
	ds_read_b128 v[114:117], v114 offset:55296
	v_mfma_f32_32x32x16_bf16 v[2:17], v[138:141], v[134:137], v[2:17]
	v_mfma_f32_32x32x16_bf16 v[18:33], v[126:129], v[118:121], v[18:33]
	v_mfma_f32_32x32x16_bf16 v[2:17], v[126:129], v[122:125], v[2:17]
	v_lshlrev_b32_e32 v128, 7, v164
	v_or_b32_e32 v126, v128, v168
	v_ashrrev_i32_e32 v127, 31, v126
	v_lshlrev_b64 v[130:131], 2, v[126:127]
	v_lshl_or_b32 v122, v169, 2, v166
	v_or_b32_e32 v124, s3, v168
	v_mov_b32_e32 v125, s5
	s_waitcnt lgkmcnt(0)
	v_mfma_f32_32x32x16_bf16 v[18:33], v[114:117], v[106:109], v[18:33]
	v_bitop3_b32 v106, v169, v167, 10 bitop3:0x36
	v_lshl_add_u32 v106, v106, 4, v165
	ds_read_b128 v[106:109], v106 offset:55296
	v_lshl_add_u64 v[132:133], s[6:7], 0, v[130:131]
	v_lshl_add_u64 v[130:131], s[92:93], 0, v[130:131]
	v_ashrrev_i32_e32 v123, 31, v122
	v_lshlrev_b64 v[122:123], 1, v[122:123]
	v_mfma_f32_32x32x16_bf16 v[2:17], v[114:117], v[110:113], v[2:17]
	s_add_i32 s3, s3, s18
	s_cmpk_gt_i32 s4, 0x7f
	s_waitcnt lgkmcnt(0)
	v_mfma_f32_32x32x16_bf16 v[18:33], v[106:109], v[98:101], v[18:33]
	v_bitop3_b32 v98, v169, v167, 12 bitop3:0x36
	v_lshl_add_u32 v98, v98, 4, v165
	ds_read_b128 v[98:101], v98 offset:55296
	v_mfma_f32_32x32x16_bf16 v[2:17], v[106:109], v[102:105], v[2:17]
	s_waitcnt lgkmcnt(0)
	v_mfma_f32_32x32x16_bf16 v[2:17], v[98:101], v[94:97], v[2:17]
	v_bitop3_b32 v94, v169, v167, 14 bitop3:0x36
	v_lshl_add_u32 v94, v94, 4, v165
	ds_read_b128 v[94:97], v94 offset:55296
	v_ashrrev_i32_e32 v167, 31, v166
	s_waitcnt lgkmcnt(0)
	v_mfma_f32_32x32x16_bf16 v[2:17], v[94:97], v[90:93], v[2:17]
	v_lshlrev_b64 v[90:91], 2, v[166:167]
	v_lshl_add_u64 v[92:93], s[10:11], 0, v[90:91]
	v_lshl_add_u64 v[90:91], s[40:41], 0, v[90:91]
	v_lshl_add_u64 v[92:93], v[92:93], 0, v[154:155]
	v_lshl_add_u64 v[94:95], v[90:91], 0, v[154:155]
	global_load_dwordx4 v[114:117], v[92:93], off
	global_load_dwordx4 v[118:121], v[94:95], off
	global_load_dwordx4 v[106:109], v[92:93], off offset:32
	global_load_dwordx4 v[110:113], v[94:95], off offset:32
	global_load_dwordx4 v[98:101], v[92:93], off offset:64
	global_load_dwordx4 v[102:105], v[94:95], off offset:64
	s_nop 0
	global_load_dwordx4 v[90:93], v[92:93], off offset:96
	s_nop 0
	global_load_dwordx4 v[94:97], v[94:95], off offset:96
	s_nop 0
	global_load_dword v186, v[132:133], off
	global_load_dword v187, v[132:133], off offset:128
	global_load_dword v188, v[132:133], off offset:256
	global_load_dword v189, v[132:133], off offset:384
	global_load_dword v190, v[130:131], off
	global_load_dword v191, v[130:131], off offset:128
	global_load_dword v192, v[130:131], off offset:256
	global_load_dword v193, v[130:131], off offset:384
	v_lshlrev_b64 v[176:177], 11, v[124:125]
	v_lshl_add_u64 v[176:177], s[62:63], 0, v[176:177]
	v_lshl_add_u64 v[176:177], v[176:177], 0, v[122:123]
	v_bfe_u32 v195, v0, 5, 1
	v_lshlrev_b32_e32 v195, 3, v195
	v_add_co_u32_e32 v176, vcc, v176, v195
	s_nop 1
	v_addc_co_u32_e32 v177, vcc, 0, v177, vcc
	v_add_co_u32_e32 v178, vcc, 0x10000, v176
	s_nop 1
	v_addc_co_u32_e32 v179, vcc, 0, v177, vcc
	v_add_co_u32_e32 v182, vcc, 0x20000, v176
	s_nop 1
	v_addc_co_u32_e32 v183, vcc, 0, v177, vcc
	v_add_co_u32_e32 v184, vcc, 0x30000, v176
	s_nop 1
	v_addc_co_u32_e32 v185, vcc, 0, v177, vcc
	s_waitcnt vmcnt(0)
	s_nop 1
	v_permlane32_swap_b32 v216, v218
	v_permlane32_swap_b32 v217, v219
	v_permlane32_swap_b32 v220, v222
	v_permlane32_swap_b32 v221, v223
	v_permlane32_swap_b32 v224, v226
	v_permlane32_swap_b32 v225, v227
	v_permlane32_swap_b32 v228, v230
	v_permlane32_swap_b32 v229, v231
	v_permlane32_swap_b32 v232, v234
	v_permlane32_swap_b32 v233, v235
	v_permlane32_swap_b32 v236, v238
	v_permlane32_swap_b32 v237, v239
	v_permlane32_swap_b32 v252, v254
	v_permlane32_swap_b32 v253, v255
	v_mul_f32_e32 v194, v118, v186
	v_fmac_f32_e32 v194, v50, v114
	v_add_f32_e32 v50, v190, v194
	v_lshlrev_b32_e32 v195, 16, v216
	v_mul_f32_e32 v50, v50, v195
	v_mul_f32_e32 v194, v119, v186
	v_fmac_f32_e32 v194, v51, v115
	v_add_f32_e32 v51, v190, v194
	v_and_b32_e32 v195, 0xffff0000, v216
	v_mul_f32_e32 v51, v51, v195
	v_mul_f32_e32 v194, v120, v186
	v_fmac_f32_e32 v194, v52, v116
	v_add_f32_e32 v52, v190, v194
	v_lshlrev_b32_e32 v195, 16, v217
	v_mul_f32_e32 v52, v52, v195
	v_mul_f32_e32 v194, v121, v186
	v_fmac_f32_e32 v194, v53, v117
	v_add_f32_e32 v53, v190, v194
	v_and_b32_e32 v195, 0xffff0000, v217
	v_mul_f32_e32 v53, v53, v195
	v_cvt_pk_bf16_f32 v50, v50, v51
	v_cvt_pk_bf16_f32 v51, v52, v53
	v_mul_f32_e32 v194, v110, v186
	v_fmac_f32_e32 v194, v54, v106
	v_add_f32_e32 v54, v190, v194
	v_lshlrev_b32_e32 v195, 16, v218
	v_mul_f32_e32 v54, v54, v195
	v_mul_f32_e32 v194, v111, v186
	v_fmac_f32_e32 v194, v55, v107
	v_add_f32_e32 v55, v190, v194
	v_and_b32_e32 v195, 0xffff0000, v218
	v_mul_f32_e32 v55, v55, v195
	v_mul_f32_e32 v194, v112, v186
	v_fmac_f32_e32 v194, v56, v108
	v_add_f32_e32 v56, v190, v194
	v_lshlrev_b32_e32 v195, 16, v219
	v_mul_f32_e32 v56, v56, v195
	v_mul_f32_e32 v194, v113, v186
	v_fmac_f32_e32 v194, v57, v109
	v_add_f32_e32 v57, v190, v194
	v_and_b32_e32 v195, 0xffff0000, v219
	v_mul_f32_e32 v57, v57, v195
	v_cvt_pk_bf16_f32 v52, v54, v55
	v_cvt_pk_bf16_f32 v53, v56, v57
	s_nop 1
	v_permlane32_swap_b32 v50, v52
	v_permlane32_swap_b32 v51, v53
	global_store_dwordx4 v[176:177], v[50:53], off offset:1536
	v_mul_f32_e32 v194, v102, v186
	v_fmac_f32_e32 v194, v58, v98
	v_add_f32_e32 v58, v190, v194
	v_lshlrev_b32_e32 v195, 16, v220
	v_mul_f32_e32 v58, v58, v195
	v_mul_f32_e32 v194, v103, v186
	v_fmac_f32_e32 v194, v59, v99
	v_add_f32_e32 v59, v190, v194
	v_and_b32_e32 v195, 0xffff0000, v220
	v_mul_f32_e32 v59, v59, v195
	v_mul_f32_e32 v194, v104, v186
	v_fmac_f32_e32 v194, v60, v100
	v_add_f32_e32 v60, v190, v194
	v_lshlrev_b32_e32 v195, 16, v221
	v_mul_f32_e32 v60, v60, v195
	v_mul_f32_e32 v194, v105, v186
	v_fmac_f32_e32 v194, v61, v101
	v_add_f32_e32 v61, v190, v194
	v_and_b32_e32 v195, 0xffff0000, v221
	v_mul_f32_e32 v61, v61, v195
	v_cvt_pk_bf16_f32 v58, v58, v59
	v_cvt_pk_bf16_f32 v59, v60, v61
	v_mul_f32_e32 v194, v94, v186
	v_fmac_f32_e32 v194, v62, v90
	v_add_f32_e32 v62, v190, v194
	v_lshlrev_b32_e32 v195, 16, v222
	v_mul_f32_e32 v62, v62, v195
	v_mul_f32_e32 v194, v95, v186
	v_fmac_f32_e32 v194, v63, v91
	v_add_f32_e32 v63, v190, v194
	v_and_b32_e32 v195, 0xffff0000, v222
	v_mul_f32_e32 v63, v63, v195
	v_mul_f32_e32 v194, v96, v186
	v_fmac_f32_e32 v194, v64, v92
	v_add_f32_e32 v64, v190, v194
	v_lshlrev_b32_e32 v195, 16, v223
	v_mul_f32_e32 v64, v64, v195
	v_mul_f32_e32 v194, v97, v186
	v_fmac_f32_e32 v194, v65, v93
	v_add_f32_e32 v65, v190, v194
	v_and_b32_e32 v195, 0xffff0000, v223
	v_mul_f32_e32 v65, v65, v195
	v_cvt_pk_bf16_f32 v60, v62, v63
	v_cvt_pk_bf16_f32 v61, v64, v65
	s_nop 1
	v_permlane32_swap_b32 v58, v60
	v_permlane32_swap_b32 v59, v61
	global_store_dwordx4 v[176:177], v[58:61], off offset:1568
	v_mul_f32_e32 v194, v118, v187
	v_fmac_f32_e32 v194, v34, v114
	v_add_f32_e32 v34, v191, v194
	v_lshlrev_b32_e32 v195, 16, v224
	v_mul_f32_e32 v34, v34, v195
	v_mul_f32_e32 v194, v119, v187
	v_fmac_f32_e32 v194, v35, v115
	v_add_f32_e32 v35, v191, v194
	v_and_b32_e32 v195, 0xffff0000, v224
	v_mul_f32_e32 v35, v35, v195
	v_mul_f32_e32 v194, v120, v187
	v_fmac_f32_e32 v194, v36, v116
	v_add_f32_e32 v36, v191, v194
	v_lshlrev_b32_e32 v195, 16, v225
	v_mul_f32_e32 v36, v36, v195
	v_mul_f32_e32 v194, v121, v187
	v_fmac_f32_e32 v194, v37, v117
	v_add_f32_e32 v37, v191, v194
	v_and_b32_e32 v195, 0xffff0000, v225
	v_mul_f32_e32 v37, v37, v195
	v_cvt_pk_bf16_f32 v34, v34, v35
	v_cvt_pk_bf16_f32 v35, v36, v37
	v_mul_f32_e32 v194, v110, v187
	v_fmac_f32_e32 v194, v38, v106
	v_add_f32_e32 v38, v191, v194
	v_lshlrev_b32_e32 v195, 16, v226
	v_mul_f32_e32 v38, v38, v195
	v_mul_f32_e32 v194, v111, v187
	v_fmac_f32_e32 v194, v39, v107
	v_add_f32_e32 v39, v191, v194
	v_and_b32_e32 v195, 0xffff0000, v226
	v_mul_f32_e32 v39, v39, v195
	v_mul_f32_e32 v194, v112, v187
	v_fmac_f32_e32 v194, v40, v108
	v_add_f32_e32 v40, v191, v194
	v_lshlrev_b32_e32 v195, 16, v227
	v_mul_f32_e32 v40, v40, v195
	v_mul_f32_e32 v194, v113, v187
	v_fmac_f32_e32 v194, v41, v109
	v_add_f32_e32 v41, v191, v194
	v_and_b32_e32 v195, 0xffff0000, v227
	v_mul_f32_e32 v41, v41, v195
	v_cvt_pk_bf16_f32 v36, v38, v39
	v_cvt_pk_bf16_f32 v37, v40, v41
	s_nop 1
	v_permlane32_swap_b32 v34, v36
	v_permlane32_swap_b32 v35, v37
	global_store_dwordx4 v[178:179], v[34:37], off offset:1536
	v_mul_f32_e32 v194, v102, v187
	v_fmac_f32_e32 v194, v42, v98
	v_add_f32_e32 v42, v191, v194
	v_lshlrev_b32_e32 v195, 16, v228
	v_mul_f32_e32 v42, v42, v195
	v_mul_f32_e32 v194, v103, v187
	v_fmac_f32_e32 v194, v43, v99
	v_add_f32_e32 v43, v191, v194
	v_and_b32_e32 v195, 0xffff0000, v228
	v_mul_f32_e32 v43, v43, v195
	v_mul_f32_e32 v194, v104, v187
	v_fmac_f32_e32 v194, v44, v100
	v_add_f32_e32 v44, v191, v194
	v_lshlrev_b32_e32 v195, 16, v229
	v_mul_f32_e32 v44, v44, v195
	v_mul_f32_e32 v194, v105, v187
	v_fmac_f32_e32 v194, v45, v101
	v_add_f32_e32 v45, v191, v194
	v_and_b32_e32 v195, 0xffff0000, v229
	v_mul_f32_e32 v45, v45, v195
	v_cvt_pk_bf16_f32 v42, v42, v43
	v_cvt_pk_bf16_f32 v43, v44, v45
	v_mul_f32_e32 v194, v94, v187
	v_fmac_f32_e32 v194, v46, v90
	v_add_f32_e32 v46, v191, v194
	v_lshlrev_b32_e32 v195, 16, v230
	v_mul_f32_e32 v46, v46, v195
	v_mul_f32_e32 v194, v95, v187
	v_fmac_f32_e32 v194, v47, v91
	v_add_f32_e32 v47, v191, v194
	v_and_b32_e32 v195, 0xffff0000, v230
	v_mul_f32_e32 v47, v47, v195
	v_mul_f32_e32 v194, v96, v187
	v_fmac_f32_e32 v194, v48, v92
	v_add_f32_e32 v48, v191, v194
	v_lshlrev_b32_e32 v195, 16, v231
	v_mul_f32_e32 v48, v48, v195
	v_mul_f32_e32 v194, v97, v187
	v_fmac_f32_e32 v194, v49, v93
	v_add_f32_e32 v49, v191, v194
	v_and_b32_e32 v195, 0xffff0000, v231
	v_mul_f32_e32 v49, v49, v195
	v_cvt_pk_bf16_f32 v44, v46, v47
	v_cvt_pk_bf16_f32 v45, v48, v49
	s_nop 1
	v_permlane32_swap_b32 v42, v44
	v_permlane32_swap_b32 v43, v45
	global_store_dwordx4 v[178:179], v[42:45], off offset:1568
	v_mul_f32_e32 v194, v118, v188
	v_fmac_f32_e32 v194, v18, v114
	v_add_f32_e32 v18, v192, v194
	v_lshlrev_b32_e32 v195, 16, v232
	v_mul_f32_e32 v18, v18, v195
	v_mul_f32_e32 v194, v119, v188
	v_fmac_f32_e32 v194, v19, v115
	v_add_f32_e32 v19, v192, v194
	v_and_b32_e32 v195, 0xffff0000, v232
	v_mul_f32_e32 v19, v19, v195
	v_mul_f32_e32 v194, v120, v188
	v_fmac_f32_e32 v194, v20, v116
	v_add_f32_e32 v20, v192, v194
	v_lshlrev_b32_e32 v195, 16, v233
	v_mul_f32_e32 v20, v20, v195
	v_mul_f32_e32 v194, v121, v188
	v_fmac_f32_e32 v194, v21, v117
	v_add_f32_e32 v21, v192, v194
	v_and_b32_e32 v195, 0xffff0000, v233
	v_mul_f32_e32 v21, v21, v195
	v_cvt_pk_bf16_f32 v18, v18, v19
	v_cvt_pk_bf16_f32 v19, v20, v21
	v_mul_f32_e32 v194, v110, v188
	v_fmac_f32_e32 v194, v22, v106
	v_add_f32_e32 v22, v192, v194
	v_lshlrev_b32_e32 v195, 16, v234
	v_mul_f32_e32 v22, v22, v195
	v_mul_f32_e32 v194, v111, v188
	v_fmac_f32_e32 v194, v23, v107
	v_add_f32_e32 v23, v192, v194
	v_and_b32_e32 v195, 0xffff0000, v234
	v_mul_f32_e32 v23, v23, v195
	v_mul_f32_e32 v194, v112, v188
	v_fmac_f32_e32 v194, v24, v108
	v_add_f32_e32 v24, v192, v194
	v_lshlrev_b32_e32 v195, 16, v235
	v_mul_f32_e32 v24, v24, v195
	v_mul_f32_e32 v194, v113, v188
	v_fmac_f32_e32 v194, v25, v109
	v_add_f32_e32 v25, v192, v194
	v_and_b32_e32 v195, 0xffff0000, v235
	v_mul_f32_e32 v25, v25, v195
	v_cvt_pk_bf16_f32 v20, v22, v23
	v_cvt_pk_bf16_f32 v21, v24, v25
	s_nop 1
	v_permlane32_swap_b32 v18, v20
	v_permlane32_swap_b32 v19, v21
	global_store_dwordx4 v[182:183], v[18:21], off offset:1536
	v_mul_f32_e32 v194, v102, v188
	v_fmac_f32_e32 v194, v26, v98
	v_add_f32_e32 v26, v192, v194
	v_lshlrev_b32_e32 v195, 16, v236
	v_mul_f32_e32 v26, v26, v195
	v_mul_f32_e32 v194, v103, v188
	v_fmac_f32_e32 v194, v27, v99
	v_add_f32_e32 v27, v192, v194
	v_and_b32_e32 v195, 0xffff0000, v236
	v_mul_f32_e32 v27, v27, v195
	v_mul_f32_e32 v194, v104, v188
	v_fmac_f32_e32 v194, v28, v100
	v_add_f32_e32 v28, v192, v194
	v_lshlrev_b32_e32 v195, 16, v237
	v_mul_f32_e32 v28, v28, v195
	v_mul_f32_e32 v194, v105, v188
	v_fmac_f32_e32 v194, v29, v101
	v_add_f32_e32 v29, v192, v194
	v_and_b32_e32 v195, 0xffff0000, v237
	v_mul_f32_e32 v29, v29, v195
	v_cvt_pk_bf16_f32 v26, v26, v27
	v_cvt_pk_bf16_f32 v27, v28, v29
	v_mul_f32_e32 v194, v94, v188
	v_fmac_f32_e32 v194, v30, v90
	v_add_f32_e32 v30, v192, v194
	v_lshlrev_b32_e32 v195, 16, v238
	v_mul_f32_e32 v30, v30, v195
	v_mul_f32_e32 v194, v95, v188
	v_fmac_f32_e32 v194, v31, v91
	v_add_f32_e32 v31, v192, v194
	v_and_b32_e32 v195, 0xffff0000, v238
	v_mul_f32_e32 v31, v31, v195
	v_mul_f32_e32 v194, v96, v188
	v_fmac_f32_e32 v194, v32, v92
	v_add_f32_e32 v32, v192, v194
	v_lshlrev_b32_e32 v195, 16, v239
	v_mul_f32_e32 v32, v32, v195
	v_mul_f32_e32 v194, v97, v188
	v_fmac_f32_e32 v194, v33, v93
	v_add_f32_e32 v33, v192, v194
	v_and_b32_e32 v195, 0xffff0000, v239
	v_mul_f32_e32 v33, v33, v195
	v_cvt_pk_bf16_f32 v28, v30, v31
	v_cvt_pk_bf16_f32 v29, v32, v33
	s_nop 1
	v_permlane32_swap_b32 v26, v28
	v_permlane32_swap_b32 v27, v29
	global_store_dwordx4 v[182:183], v[26:29], off offset:1568
	v_mul_f32_e32 v194, v118, v189
	v_fmac_f32_e32 v194, v2, v114
	v_add_f32_e32 v2, v193, v194
	v_lshlrev_b32_e32 v195, 16, v252
	v_mul_f32_e32 v2, v2, v195
	v_mul_f32_e32 v194, v119, v189
	v_fmac_f32_e32 v194, v3, v115
	v_add_f32_e32 v3, v193, v194
	v_and_b32_e32 v195, 0xffff0000, v252
	v_mul_f32_e32 v3, v3, v195
	v_mul_f32_e32 v194, v120, v189
	v_fmac_f32_e32 v194, v4, v116
	v_add_f32_e32 v4, v193, v194
	v_lshlrev_b32_e32 v195, 16, v253
	v_mul_f32_e32 v4, v4, v195
	v_mul_f32_e32 v194, v121, v189
	v_fmac_f32_e32 v194, v5, v117
	v_add_f32_e32 v5, v193, v194
	v_and_b32_e32 v195, 0xffff0000, v253
	v_mul_f32_e32 v5, v5, v195
	v_cvt_pk_bf16_f32 v2, v2, v3
	v_cvt_pk_bf16_f32 v3, v4, v5
	v_mul_f32_e32 v194, v110, v189
	v_fmac_f32_e32 v194, v6, v106
	v_add_f32_e32 v6, v193, v194
	v_lshlrev_b32_e32 v195, 16, v254
	v_mul_f32_e32 v6, v6, v195
	v_mul_f32_e32 v194, v111, v189
	v_fmac_f32_e32 v194, v7, v107
	v_add_f32_e32 v7, v193, v194
	v_and_b32_e32 v195, 0xffff0000, v254
	v_mul_f32_e32 v7, v7, v195
	v_mul_f32_e32 v194, v112, v189
	v_fmac_f32_e32 v194, v8, v108
	v_add_f32_e32 v8, v193, v194
	v_lshlrev_b32_e32 v195, 16, v255
	v_mul_f32_e32 v8, v8, v195
	v_mul_f32_e32 v194, v113, v189
	v_fmac_f32_e32 v194, v9, v109
	v_add_f32_e32 v9, v193, v194
	v_and_b32_e32 v195, 0xffff0000, v255
	v_mul_f32_e32 v9, v9, v195
	v_cvt_pk_bf16_f32 v4, v6, v7
	v_cvt_pk_bf16_f32 v5, v8, v9
	s_nop 1
	v_permlane32_swap_b32 v2, v4
	v_permlane32_swap_b32 v3, v5
	global_store_dwordx4 v[184:185], v[2:5], off offset:1536
	v_mul_f32_e32 v194, v102, v189
	v_fmac_f32_e32 v194, v10, v98
	v_add_f32_e32 v10, v193, v194
	v_lshlrev_b32_e32 v195, 16, v240
	v_mul_f32_e32 v10, v10, v195
	v_mul_f32_e32 v194, v103, v189
	v_fmac_f32_e32 v194, v11, v99
	v_add_f32_e32 v11, v193, v194
	v_and_b32_e32 v195, 0xffff0000, v240
	v_mul_f32_e32 v11, v11, v195
	v_mul_f32_e32 v194, v104, v189
	v_fmac_f32_e32 v194, v12, v100
	v_add_f32_e32 v12, v193, v194
	v_lshlrev_b32_e32 v195, 16, v241
	v_mul_f32_e32 v12, v12, v195
	v_mul_f32_e32 v194, v105, v189
	v_fmac_f32_e32 v194, v13, v101
	v_add_f32_e32 v13, v193, v194
	v_and_b32_e32 v195, 0xffff0000, v241
	v_mul_f32_e32 v13, v13, v195
	v_cvt_pk_bf16_f32 v10, v10, v11
	v_cvt_pk_bf16_f32 v11, v12, v13
	v_mul_f32_e32 v194, v94, v189
	v_fmac_f32_e32 v194, v14, v90
	v_add_f32_e32 v14, v193, v194
	v_lshlrev_b32_e32 v195, 16, v246
	v_mul_f32_e32 v14, v14, v195
	v_mul_f32_e32 v194, v95, v189
	v_fmac_f32_e32 v194, v15, v91
	v_add_f32_e32 v15, v193, v194
	v_and_b32_e32 v195, 0xffff0000, v246
	v_mul_f32_e32 v15, v15, v195
	v_mul_f32_e32 v194, v96, v189
	v_fmac_f32_e32 v194, v16, v92
	v_add_f32_e32 v16, v193, v194
	v_lshlrev_b32_e32 v195, 16, v247
	v_mul_f32_e32 v16, v16, v195
	v_mul_f32_e32 v194, v97, v189
	v_fmac_f32_e32 v194, v17, v93
	v_add_f32_e32 v17, v193, v194
	v_and_b32_e32 v195, 0xffff0000, v247
	v_mul_f32_e32 v17, v17, v195
	v_cvt_pk_bf16_f32 v12, v14, v15
	v_cvt_pk_bf16_f32 v13, v16, v17
	s_nop 1
	v_permlane32_swap_b32 v10, v12
	v_permlane32_swap_b32 v11, v13
	global_store_dwordx4 v[184:185], v[10:13], off offset:1568
	s_barrier
	s_cbranch_scc0 .LBB0_779

.LBB0_849:
	v_mov_b32_e32 v43, v0
	s_ashr_i32 s5, s3, 31
	v_ashrrev_i32_e32 v44, 7, v43
	s_waitcnt vmcnt(7)
	v_add_u32_e32 v130, s2, v44
	v_ashrrev_i32_e32 v131, 31, v130
	v_and_b32_e32 v134, 31, v43
	s_waitcnt vmcnt(0)
	v_lshlrev_b64 v[2:3], 15, v[130:131]
	v_bfe_u32 v135, v43, 5, 1
	v_lshl_add_u64 v[2:3], s[56:57], 0, v[2:3]
	v_lshlrev_b32_e32 v154, 8, v134
	v_lshl_add_u64 v[2:3], v[2:3], 0, v[154:155]
	v_lshlrev_b32_e32 v154, 4, v135
	v_lshl_add_u64 v[18:19], v[2:3], 0, v[154:155]
	v_add_co_u32_e32 v20, vcc, s14, v18
	v_ashrrev_i32_e32 v45, 2, v43
	s_nop 0
	v_addc_co_u32_e32 v21, vcc, 0, v19, vcc
	v_add_co_u32_e32 v22, vcc, s17, v18
	global_load_dwordx4 v[2:5], v[18:19], off
	global_load_dwordx4 v[6:9], v[20:21], off
	v_addc_co_u32_e32 v23, vcc, 0, v19, vcc
	v_add_co_u32_e32 v24, vcc, s30, v18
	global_load_dwordx4 v[10:13], v[22:23], off
	s_nop 0
	v_addc_co_u32_e32 v25, vcc, 0, v19, vcc
	global_load_dwordx4 v[14:17], v[24:25], off
	global_load_dwordx4 v[114:117], v[18:19], off offset:32
	global_load_dwordx4 v[118:121], v[20:21], off offset:32
	global_load_dwordx4 v[122:125], v[22:23], off offset:32
	global_load_dwordx4 v[126:129], v[24:25], off offset:32
	global_load_dwordx4 v[102:105], v[20:21], off offset:64
	global_load_dwordx4 v[106:109], v[22:23], off offset:64
	global_load_dwordx4 v[110:113], v[24:25], off offset:64
	global_load_dwordx4 v[90:93], v[20:21], off offset:96
	global_load_dwordx4 v[94:97], v[22:23], off offset:96
	global_load_dwordx4 v[98:101], v[24:25], off offset:96
	global_load_dwordx4 v[82:85], v[22:23], off offset:128
	global_load_dwordx4 v[86:89], v[24:25], off offset:128
	global_load_dwordx4 v[74:77], v[22:23], off offset:160
	global_load_dwordx4 v[78:81], v[24:25], off offset:160
	global_load_dwordx4 v[70:73], v[24:25], off offset:192
	global_load_dwordx4 v[66:69], v[24:25], off offset:224
	v_add_u32_e32 v18, s3, v45
	v_ashrrev_i32_e32 v19, 31, v18
	v_lshlrev_b32_e32 v20, 6, v43
	v_lshlrev_b64 v[18:19], 12, v[18:19]
	v_and_b32_e32 v46, 0xc0, v20
	v_lshl_add_u64 v[18:19], s[60:61], 0, v[18:19]
	v_lshlrev_b32_e32 v20, 1, v46
	v_mov_b32_e32 v21, v155
	v_lshl_add_u64 v[34:35], v[18:19], 0, v[20:21]
	global_load_dwordx4 v[18:21], v[34:35], off offset:3632
	global_load_dwordx4 v[22:25], v[34:35], off offset:3616
	global_load_dwordx4 v[26:29], v[34:35], off offset:3600
	global_load_dwordx4 v[30:33], v[34:35], off offset:3584
	global_load_dwordx4 v[36:39], v[34:35], off offset:3680
	global_load_dwordx4 v[176:179], v[34:35], off offset:3664
	global_load_dwordx4 v[48:51], v[34:35], off offset:3648
	global_load_dwordx4 v[182:185], v[34:35], off offset:3696
	v_and_b32_e32 v215, 31, v0
	v_add_u32_e32 v215, s3, v215
	v_lshlrev_b32_e32 v215, 12, v215
	v_and_b32_e32 v245, 0x1c0, v0
	v_add_u32_e32 v215, v215, v245
	v_bfe_u32 v245, v0, 5, 1
	v_lshl_add_u32 v245, v245, 3, v215
	v_bfe_u32 v215, v0, 5, 1
	v_lshl_add_u32 v215, v215, 3, v245
	global_load_dwordx4 v[216:219], v215, s[60:61] offset:3072
	global_load_dwordx4 v[220:223], v215, s[60:61] offset:3104
	s_add_u32 s98, s60, 0x20000
	s_addc_u32 s99, s61, 0
	global_load_dwordx4 v[224:227], v215, s[98:99] offset:3072
	global_load_dwordx4 v[228:231], v215, s[98:99] offset:3104
	s_add_u32 s100, s60, 0x40000
	s_addc_u32 s101, s61, 0
	global_load_dwordx4 v[232:235], v215, s[100:101] offset:3072
	global_load_dwordx4 v[236:239], v215, s[100:101] offset:3104
	s_add_u32 s98, s60, 0x60000
	s_addc_u32 s99, s61, 0
	global_load_dwordx4 v[252:255], v215, s[98:99] offset:3072
	global_load_dwordx2 v[240:241], v245, s[98:99] offset:3104
	global_load_dwordx2 v[246:247], v245, s[98:99] offset:3120
	v_lshrrev_b32_e32 v42, 5, v43
	s_add_i32 s4, s4, s46
	s_waitcnt vmcnt(16)
	v_lshlrev_b32_e32 v144, 16, v18
	s_waitcnt vmcnt(15)
	v_lshlrev_b32_e32 v150, 16, v22
	s_waitcnt vmcnt(14)
	v_lshlrev_b32_e32 v168, 16, v26
	s_waitcnt vmcnt(13)
	v_lshlrev_b32_e32 v174, 16, v30
	v_and_b32_e32 v173, 0xffff0000, v30
	v_add_f32_e32 v30, 0, v174
	v_lshlrev_b32_e32 v172, 16, v31
	v_add_f32_e32 v30, v30, v173
	v_and_b32_e32 v171, 0xffff0000, v31
	v_mul_f32_e32 v31, v173, v173
	v_add_f32_e32 v30, v30, v172
	v_lshlrev_b32_e32 v170, 16, v32
	v_fmac_f32_e32 v31, v174, v174
	v_add_f32_e32 v30, v30, v171
	v_and_b32_e32 v169, 0xffff0000, v32
	v_fmac_f32_e32 v31, v172, v172
	v_add_f32_e32 v30, v30, v170
	v_lshlrev_b32_e32 v167, 16, v33
	v_fmac_f32_e32 v31, v171, v171
	v_add_f32_e32 v30, v30, v169
	v_and_b32_e32 v165, 0xffff0000, v33
	v_fmac_f32_e32 v31, v170, v170
	v_add_f32_e32 v30, v30, v167
	v_fmac_f32_e32 v31, v169, v169
	v_add_f32_e32 v30, v30, v165
	v_fmac_f32_e32 v31, v167, v167
	v_and_b32_e32 v166, 0xffff0000, v26
	v_add_f32_e32 v26, v30, v168
	v_fmac_f32_e32 v31, v165, v165
	v_lshlrev_b32_e32 v164, 16, v27
	v_add_f32_e32 v26, v26, v166
	v_and_b32_e32 v153, 0xffff0000, v27
	v_fmac_f32_e32 v31, v168, v168
	v_add_f32_e32 v26, v26, v164
	v_lshlrev_b32_e32 v152, 16, v28
	v_fmac_f32_e32 v31, v166, v166
	v_add_f32_e32 v26, v26, v153
	v_and_b32_e32 v151, 0xffff0000, v28
	v_fmac_f32_e32 v31, v164, v164
	v_add_f32_e32 v26, v26, v152
	v_lshlrev_b32_e32 v148, 16, v29
	v_fmac_f32_e32 v31, v153, v153
	v_add_f32_e32 v26, v26, v151
	v_and_b32_e32 v146, 0xffff0000, v29
	v_fmac_f32_e32 v31, v152, v152
	v_add_f32_e32 v26, v26, v148
	v_fmac_f32_e32 v31, v151, v151
	v_add_f32_e32 v26, v26, v146
	v_fmac_f32_e32 v31, v148, v148
	v_and_b32_e32 v149, 0xffff0000, v22
	v_add_f32_e32 v22, v26, v150
	v_fmac_f32_e32 v31, v146, v146
	v_lshlrev_b32_e32 v147, 16, v23
	v_add_f32_e32 v22, v22, v149
	v_and_b32_e32 v145, 0xffff0000, v23
	v_fmac_f32_e32 v31, v150, v150
	v_add_f32_e32 v22, v22, v147
	v_lshlrev_b32_e32 v143, 16, v24
	v_fmac_f32_e32 v31, v149, v149
	v_add_f32_e32 v22, v22, v145
	v_and_b32_e32 v141, 0xffff0000, v24
	v_fmac_f32_e32 v31, v147, v147
	v_add_f32_e32 v22, v22, v143
	v_lshlrev_b32_e32 v139, 16, v25
	v_fmac_f32_e32 v31, v145, v145
	v_add_f32_e32 v22, v22, v141
	v_and_b32_e32 v137, 0xffff0000, v25
	v_fmac_f32_e32 v31, v143, v143
	v_add_f32_e32 v22, v22, v139
	v_fmac_f32_e32 v31, v141, v141
	v_add_f32_e32 v22, v22, v137
	v_fmac_f32_e32 v31, v139, v139
	v_and_b32_e32 v142, 0xffff0000, v18
	v_add_f32_e32 v18, v22, v144
	v_fmac_f32_e32 v31, v137, v137
	v_lshlrev_b32_e32 v140, 16, v19
	v_add_f32_e32 v18, v18, v142
	v_and_b32_e32 v138, 0xffff0000, v19
	v_fmac_f32_e32 v31, v144, v144
	v_add_f32_e32 v18, v18, v140
	v_lshlrev_b32_e32 v133, 16, v20
	v_fmac_f32_e32 v31, v142, v142
	v_add_f32_e32 v18, v18, v138
	v_and_b32_e32 v131, 0xffff0000, v20
	v_fmac_f32_e32 v31, v140, v140
	v_add_f32_e32 v18, v18, v133
	v_lshlrev_b32_e32 v64, 16, v21
	v_fmac_f32_e32 v31, v138, v138
	v_add_f32_e32 v18, v18, v131
	v_and_b32_e32 v62, 0xffff0000, v21
	v_fmac_f32_e32 v31, v133, v133
	v_add_f32_e32 v18, v18, v64
	v_fmac_f32_e32 v31, v131, v131
	v_add_f32_e32 v18, v18, v62
	s_waitcnt vmcnt(10)
	v_lshlrev_b32_e32 v136, 16, v48
	v_fmac_f32_e32 v31, v64, v64
	v_and_b32_e32 v132, 0xffff0000, v48
	v_add_f32_e32 v18, v18, v136
	v_fmac_f32_e32 v31, v62, v62
	v_lshlrev_b32_e32 v65, 16, v49
	v_add_f32_e32 v18, v18, v132
	v_and_b32_e32 v63, 0xffff0000, v49
	v_fmac_f32_e32 v31, v136, v136
	v_add_f32_e32 v18, v18, v65
	v_lshlrev_b32_e32 v60, 16, v50
	v_fmac_f32_e32 v31, v132, v132
	v_add_f32_e32 v18, v18, v63
	v_and_b32_e32 v59, 0xffff0000, v50
	v_fmac_f32_e32 v31, v65, v65
	v_add_f32_e32 v18, v18, v60
	v_lshlrev_b32_e32 v57, 16, v51
	v_fmac_f32_e32 v31, v63, v63
	v_add_f32_e32 v18, v18, v59
	v_and_b32_e32 v55, 0xffff0000, v51
	v_fmac_f32_e32 v31, v60, v60
	v_add_f32_e32 v18, v18, v57
	v_fmac_f32_e32 v31, v59, v59
	v_add_f32_e32 v18, v18, v55
	v_lshlrev_b32_e32 v61, 16, v176
	v_fmac_f32_e32 v31, v57, v57
	v_and_b32_e32 v58, 0xffff0000, v176
	v_add_f32_e32 v18, v18, v61
	v_fmac_f32_e32 v31, v55, v55
	v_lshlrev_b32_e32 v56, 16, v177
	v_add_f32_e32 v18, v18, v58
	v_and_b32_e32 v54, 0xffff0000, v177
	v_fmac_f32_e32 v31, v61, v61
	v_add_f32_e32 v18, v18, v56
	v_lshlrev_b32_e32 v53, 16, v178
	v_fmac_f32_e32 v31, v58, v58
	v_add_f32_e32 v18, v18, v54
	v_and_b32_e32 v51, 0xffff0000, v178
	v_fmac_f32_e32 v31, v56, v56
	v_add_f32_e32 v18, v18, v53
	v_lshlrev_b32_e32 v49, 16, v179
	v_fmac_f32_e32 v31, v54, v54
	v_add_f32_e32 v18, v18, v51
	v_and_b32_e32 v47, 0xffff0000, v179
	v_fmac_f32_e32 v31, v53, v53
	v_add_f32_e32 v18, v18, v49
	v_fmac_f32_e32 v31, v51, v51
	v_add_f32_e32 v18, v18, v47
	v_lshlrev_b32_e32 v52, 16, v36
	v_fmac_f32_e32 v31, v49, v49
	v_and_b32_e32 v50, 0xffff0000, v36
	v_add_f32_e32 v18, v18, v52
	v_fmac_f32_e32 v31, v47, v47
	v_lshlrev_b32_e32 v48, 16, v37
	v_add_f32_e32 v18, v18, v50
	v_fmac_f32_e32 v31, v52, v52
	v_add_f32_e32 v18, v18, v48
	v_and_b32_e32 v37, 0xffff0000, v37
	v_fmac_f32_e32 v31, v50, v50
	v_lshlrev_b32_e32 v34, 16, v38
	v_mov_b32_e32 v35, v37
	v_add_f32_e32 v20, v18, v37
	v_fmac_f32_e32 v31, v48, v48
	v_and_b32_e32 v24, 0xffff0000, v38
	v_pk_mul_f32 v[18:19], v[34:35], v[34:35]
	v_add_f32_e32 v20, v20, v34
	v_lshlrev_b32_e32 v25, 16, v39
	v_add_f32_e32 v19, v19, v31
	v_add_f32_e32 v20, v20, v24
	v_add_f32_e32 v21, v18, v19
	v_pk_mul_f32 v[18:19], v[24:25], v[24:25]
	v_add_f32_e32 v20, v20, v25
	v_and_b32_e32 v33, 0xffff0000, v39
	v_add_f32_e32 v18, v18, v21
	s_waitcnt vmcnt(9)
	v_lshlrev_b32_e32 v28, 16, v182
	v_mov_b32_e32 v29, v33
	v_add_f32_e32 v20, v20, v33
	v_add_f32_e32 v21, v19, v18
	v_and_b32_e32 v22, 0xffff0000, v182
	v_pk_mul_f32 v[18:19], v[28:29], v[28:29]
	v_add_f32_e32 v20, v20, v28
	v_lshlrev_b32_e32 v23, 16, v183
	v_add_f32_e32 v19, v19, v21
	v_add_f32_e32 v20, v20, v22
	v_add_f32_e32 v21, v18, v19
	v_pk_mul_f32 v[18:19], v[22:23], v[22:23]
	v_add_f32_e32 v29, v20, v23
	v_and_b32_e32 v31, 0xffff0000, v183
	v_add_f32_e32 v18, v18, v21
	v_lshlrev_b32_e32 v26, 16, v184
	v_mov_b32_e32 v27, v31
	v_add_f32_e32 v29, v29, v31
	v_and_b32_e32 v36, s0, v38
	v_add_f32_e32 v18, v19, v18
	v_and_b32_e32 v20, 0xffff0000, v184
	v_pk_mul_f32 v[38:39], v[26:27], v[26:27]
	v_add_f32_e32 v27, v29, v26
	v_lshlrev_b32_e32 v21, 16, v185
	v_add_f32_e32 v18, v39, v18
	v_add_f32_e32 v27, v27, v20
	v_and_b32_e32 v29, 64, v181
	v_add_f32_e32 v18, v38, v18
	v_pk_mul_f32 v[40:41], v[20:21], v[20:21]
	v_add_f32_e32 v39, v27, v21
	v_xor_b32_e32 v27, 1, v181
	v_add_u32_e32 v29, 64, v29
	v_and_b32_e32 v19, 0xffff0000, v185
	v_add_f32_e32 v18, v40, v18
	v_cmp_lt_i32_e32 vcc, v27, v29
	v_add_f32_e32 v18, v41, v18
	v_mul_f32_e32 v38, v19, v19
	v_cndmask_b32_e32 v27, v181, v27, vcc
	v_lshlrev_b32_e32 v27, 2, v27
	v_pk_add_f32 v[38:39], v[38:39], v[18:19]
	ds_bpermute_b32 v41, v27, v39
	ds_bpermute_b32 v40, v27, v38
	v_xor_b32_e32 v35, 2, v181
	v_cmp_lt_i32_e32 vcc, v35, v29
	v_and_b32_e32 v30, s0, v182
	v_mov_b32_e32 v32, v36
	v_cndmask_b32_e32 v29, v181, v35, vcc
	v_lshlrev_b32_e32 v29, 2, v29
	s_waitcnt lgkmcnt(0)
	v_pk_add_f32 v[38:39], v[38:39], v[40:41]
	ds_bpermute_b32 v41, v29, v39
	ds_bpermute_b32 v40, v29, v38
	s_waitcnt lgkmcnt(0)
	v_pk_add_f32 v[40:41], v[38:39], v[40:41]
	s_nop 0
	v_pk_mul_f32 v[38:39], v[40:41], s[22:23] op_sel_hi:[1,0]
	v_pk_fma_f32 v[36:37], v[40:41], s[22:23], v[36:37] op_sel_hi:[1,0,1] neg_lo:[1,0,0] neg_hi:[1,0,0]
	v_fma_f32 v18, -v39, v39, v38
	v_max_f32_e32 v18, 0, v18
	v_add_f32_e32 v18, 0x358637bd, v18
	v_cmp_gt_f32_e32 vcc, s33, v18
	v_mul_f32_e32 v27, 0x4b800000, v18
	v_sub_f32_e32 v29, v174, v39
	v_cndmask_b32_e32 v18, v18, v27, vcc
	v_rsq_f32_e32 v18, v18
	v_sub_f32_e32 v19, v19, v39
	v_mul_f32_e32 v27, 0x45800000, v18
	v_cndmask_b32_e32 v18, v18, v27, vcc
	v_mul_f32_e32 v29, v29, v18
	v_lshlrev_b32_e32 v27, 1, v45
	v_bfe_u32 v35, v29, 16, 1
	v_ashrrev_i32_e32 v45, 1, v43
	v_and_b32_e32 v27, 14, v27
	v_add3_u32 v29, v29, v35, s15
	v_lshl_add_u32 v35, v46, 8, 32
	v_and_b32_e32 v46, -16, v45
	v_add3_u32 v174, v35, v46, v27
	ds_write_b16_d16_hi v174, v29 offset:55296
	v_mul_f32_e64 v215, -v39, v18
	v_fma_f32 v29, v173, v18, v215
	v_cvt_pk_bf16_f32 v29, v29, v29
	v_bitop3_b32 v173, v45, 16, -16 bitop3:0x6c
	v_add3_u32 v175, v35, v173, v27
	ds_write_b16 v175, v29 offset:55552
	v_fma_f32 v29, v172, v18, v215
	v_cvt_pk_bf16_f32 v29, v29, v29
	v_bitop3_b32 v172, v45, 32, -16 bitop3:0x6c
	v_add3_u32 v176, v35, v172, v27
	ds_write_b16 v176, v29 offset:55808
	v_fma_f32 v29, v171, v18, v215
	v_cvt_pk_bf16_f32 v29, v29, v29
	v_bitop3_b32 v171, v45, 48, -16 bitop3:0x6c
	v_add3_u32 v177, v35, v171, v27
	ds_write_b16 v177, v29 offset:56064
	v_fma_f32 v29, v170, v18, v215
	v_cvt_pk_bf16_f32 v29, v29, v29
	v_bitop3_b32 v170, v45, 64, -16 bitop3:0x6c
	v_add3_u32 v178, v35, v170, v27
	ds_write_b16 v178, v29 offset:56320
	v_fma_f32 v29, v169, v18, v215
	v_cvt_pk_bf16_f32 v29, v29, v29
	v_bitop3_b32 v169, v45, s34, -16 bitop3:0x6c
	v_add3_u32 v179, v35, v169, v27
	ds_write_b16 v179, v29 offset:56576
	v_fma_f32 v29, v167, v18, v215
	v_cvt_pk_bf16_f32 v29, v29, v29
	v_bitop3_b32 v167, v45, s31, -16 bitop3:0x6c
	v_add3_u32 v182, v35, v167, v27
	ds_write_b16 v182, v29 offset:56832
	v_fma_f32 v29, v165, v18, v215
	v_cvt_pk_bf16_f32 v29, v29, v29
	v_bitop3_b32 v165, v45, s13, -16 bitop3:0x6c
	v_add3_u32 v183, v35, v165, v27
	ds_write_b16 v183, v29 offset:57088
	v_fma_f32 v29, v168, v18, v215
	v_cvt_pk_bf16_f32 v29, v29, v29
	v_bitop3_b32 v168, v45, s12, -16 bitop3:0x6c
	v_add3_u32 v184, v35, v168, v27
	ds_write_b16 v184, v29 offset:57344
	v_fma_f32 v29, v166, v18, v215
	v_cvt_pk_bf16_f32 v29, v29, v29
	v_bitop3_b32 v166, v45, s35, -16 bitop3:0x6c
	v_add3_u32 v185, v35, v166, v27
	ds_write_b16 v185, v29 offset:57600
	v_fma_f32 v29, v164, v18, v215
	v_cvt_pk_bf16_f32 v29, v29, v29
	v_bitop3_b32 v164, v45, s38, -16 bitop3:0x6c
	v_add3_u32 v186, v35, v164, v27
	ds_write_b16 v186, v29 offset:57856
	v_fma_f32 v29, v153, v18, v215
	v_cvt_pk_bf16_f32 v29, v29, v29
	v_bitop3_b32 v153, v45, s39, -16 bitop3:0x6c
	v_add3_u32 v187, v35, v153, v27
	ds_write_b16 v187, v29 offset:58112
	v_fma_f32 v29, v152, v18, v215
	v_cvt_pk_bf16_f32 v29, v29, v29
	v_bitop3_b32 v152, v45, s16, -16 bitop3:0x6c
	v_add3_u32 v188, v35, v152, v27
	ds_write_b16 v188, v29 offset:58368
	v_fma_f32 v29, v151, v18, v215
	v_cvt_pk_bf16_f32 v29, v29, v29
	v_bitop3_b32 v151, v45, s40, -16 bitop3:0x6c
	v_add3_u32 v189, v35, v151, v27
	ds_write_b16 v189, v29 offset:58624
	v_fma_f32 v29, v148, v18, v215
	v_cvt_pk_bf16_f32 v29, v29, v29
	v_bitop3_b32 v148, v45, s41, -16 bitop3:0x6c
	v_add3_u32 v190, v35, v148, v27
	ds_write_b16 v190, v29 offset:58880
	v_sub_f32_e32 v29, v146, v39
	v_mul_f32_e32 v29, v29, v18
	v_bfe_u32 v146, v29, 16, 1
	v_bitop3_b32 v45, v45, s42, -16 bitop3:0x6c
	v_add_u32_e32 v38, 0xd800, v35
	v_add3_u32 v29, v29, v146, s15
	v_add3_u32 v35, v35, v45, v27
	ds_write_b16_d16_hi v35, v29 offset:59136
	v_fma_f32 v29, v150, v18, v215
	v_cvt_pk_bf16_f32 v29, v29, v29
	ds_write_b16 v174, v29 offset:59392
	v_fma_f32 v29, v149, v18, v215
	v_cvt_pk_bf16_f32 v29, v29, v29
	ds_write_b16 v175, v29 offset:59648
	v_fma_f32 v29, v147, v18, v215
	v_cvt_pk_bf16_f32 v29, v29, v29
	ds_write_b16 v176, v29 offset:59904
	v_fma_f32 v29, v145, v18, v215
	v_cvt_pk_bf16_f32 v29, v29, v29
	ds_write_b16 v177, v29 offset:60160
	v_fma_f32 v29, v143, v18, v215
	v_cvt_pk_bf16_f32 v29, v29, v29
	ds_write_b16 v178, v29 offset:60416
	v_fma_f32 v29, v141, v18, v215
	v_cvt_pk_bf16_f32 v29, v29, v29
	ds_write_b16 v179, v29 offset:60672
	v_fma_f32 v29, v139, v18, v215
	v_cvt_pk_bf16_f32 v29, v29, v29
	ds_write_b16 v182, v29 offset:60928
	v_fma_f32 v29, v137, v18, v215
	v_cvt_pk_bf16_f32 v29, v29, v29
	ds_write_b16 v183, v29 offset:61184
	v_fma_f32 v29, v144, v18, v215
	v_cvt_pk_bf16_f32 v29, v29, v29
	ds_write_b16 v184, v29 offset:61440
	v_fma_f32 v29, v142, v18, v215
	v_cvt_pk_bf16_f32 v29, v29, v29
	ds_write_b16 v185, v29 offset:61696
	v_fma_f32 v29, v140, v18, v215
	v_cvt_pk_bf16_f32 v29, v29, v29
	ds_write_b16 v186, v29 offset:61952
	v_fma_f32 v29, v138, v18, v215
	v_cvt_pk_bf16_f32 v29, v29, v29
	ds_write_b16 v187, v29 offset:62208
	v_fma_f32 v29, v133, v18, v215
	v_cvt_pk_bf16_f32 v29, v29, v29
	ds_write_b16 v188, v29 offset:62464
	v_fma_f32 v29, v131, v18, v215
	v_cvt_pk_bf16_f32 v29, v29, v29
	ds_write_b16 v189, v29 offset:62720
	v_fma_f32 v29, v64, v18, v215
	v_cvt_pk_bf16_f32 v29, v29, v29
	ds_write_b16 v190, v29 offset:62976
	v_fma_f32 v29, v62, v18, v215
	v_cvt_pk_bf16_f32 v29, v29, v29
	ds_write_b16 v35, v29 offset:63232
	v_fma_f32 v29, v136, v18, v215
	v_cvt_pk_bf16_f32 v29, v29, v29
	ds_write_b16 v174, v29 offset:63488
	v_fma_f32 v29, v132, v18, v215
	v_cvt_pk_bf16_f32 v29, v29, v29
	ds_write_b16 v175, v29 offset:63744
	v_fma_f32 v29, v65, v18, v215
	v_cvt_pk_bf16_f32 v29, v29, v29
	ds_write_b16 v176, v29 offset:64000
	v_fma_f32 v29, v63, v18, v215
	v_cvt_pk_bf16_f32 v29, v29, v29
	ds_write_b16 v177, v29 offset:64256
	v_fma_f32 v29, v60, v18, v215
	v_cvt_pk_bf16_f32 v29, v29, v29
	ds_write_b16 v178, v29 offset:64512
	v_fma_f32 v29, v59, v18, v215
	v_cvt_pk_bf16_f32 v29, v29, v29
	ds_write_b16 v179, v29 offset:64768
	v_fma_f32 v29, v57, v18, v215
	v_cvt_pk_bf16_f32 v29, v29, v29
	ds_write_b16 v182, v29 offset:65024
	v_fma_f32 v29, v55, v18, v215
	v_cvt_pk_bf16_f32 v29, v29, v29
	ds_write_b16 v183, v29 offset:65280
	v_fma_f32 v29, v61, v18, v215
	v_cvt_pk_bf16_f32 v29, v29, v29
	v_add3_u32 v35, v38, v168, v27
	ds_write_b16 v35, v29 offset:10240
	v_fma_f32 v29, v58, v18, v215
	v_cvt_pk_bf16_f32 v29, v29, v29
	v_add3_u32 v55, v38, v166, v27
	ds_write_b16 v55, v29 offset:10496
	v_fma_f32 v29, v56, v18, v215
	v_cvt_pk_bf16_f32 v29, v29, v29
	v_add3_u32 v56, v38, v164, v27
	ds_write_b16 v56, v29 offset:10752
	v_fma_f32 v29, v54, v18, v215
	v_cvt_pk_bf16_f32 v29, v29, v29
	v_add3_u32 v54, v38, v153, v27
	ds_write_b16 v54, v29 offset:11008
	v_fma_f32 v29, v53, v18, v215
	v_cvt_pk_bf16_f32 v29, v29, v29
	v_add3_u32 v53, v38, v152, v27
	ds_write_b16 v53, v29 offset:11264
	v_fma_f32 v29, v51, v18, v215
	v_cvt_pk_bf16_f32 v29, v29, v29
	v_add3_u32 v51, v38, v151, v27
	ds_write_b16 v51, v29 offset:11520
	v_fma_f32 v29, v49, v18, v215
	v_cvt_pk_bf16_f32 v29, v29, v29
	v_add3_u32 v49, v38, v148, v27
	ds_write_b16 v49, v29 offset:11776
	v_fma_f32 v29, v47, v18, v215
	v_cvt_pk_bf16_f32 v29, v29, v29
	v_add3_u32 v45, v38, v45, v27
	ds_write_b16 v45, v29 offset:12032
	v_fma_f32 v29, v52, v18, v215
	v_cvt_pk_bf16_f32 v29, v29, v29
	v_add3_u32 v46, v38, v46, v27
	ds_write_b16 v46, v29 offset:12288
	v_fma_f32 v29, v50, v18, v215
	v_cvt_pk_bf16_f32 v29, v29, v29
	v_add3_u32 v46, v38, v173, v27
	ds_write_b16 v46, v29 offset:12544
	v_fma_f32 v29, v48, v18, v215
	v_cvt_pk_bf16_f32 v29, v29, v29
	v_add3_u32 v46, v38, v172, v27
	ds_write_b16 v46, v29 offset:12800
	v_mul_f32_e32 v29, v37, v18
	v_bfe_u32 v36, v29, 16, 1
	v_add3_u32 v29, v29, v36, s15
	v_add3_u32 v36, v38, v171, v27
	ds_write_b16_d16_hi v36, v29 offset:13056
	v_fma_f32 v29, v34, v18, v215
	v_cvt_pk_bf16_f32 v29, v29, v29
	v_add3_u32 v34, v38, v170, v27
	ds_write_b16 v34, v29 offset:13312
	v_sub_f32_e32 v29, v24, v39
	v_pk_fma_f32 v[24:25], v[40:41], s[22:23], v[24:25] op_sel_hi:[1,0,1] neg_lo:[1,0,0] neg_hi:[1,0,0]
	v_mul_f32_e32 v29, v29, v18
	v_mul_f32_e32 v24, v25, v18
	v_bfe_u32 v34, v29, 16, 1
	v_bfe_u32 v25, v24, 16, 1
	v_add3_u32 v29, v29, v34, s15
	v_add3_u32 v34, v38, v169, v27
	v_add3_u32 v24, v24, v25, s15
	v_add3_u32 v25, v38, v167, v27
	ds_write_b16_d16_hi v34, v29 offset:13568
	ds_write_b16_d16_hi v25, v24 offset:13824
	v_pk_fma_f32 v[24:25], v[40:41], s[22:23], v[32:33] op_sel_hi:[1,0,1] neg_lo:[1,0,0] neg_hi:[1,0,0]
	v_and_b32_e32 v133, 15, v43
	v_mul_f32_e32 v24, v25, v18
	v_bfe_u32 v25, v24, 16, 1
	v_add3_u32 v24, v24, v25, s15
	v_add3_u32 v25, v38, v165, v27
	ds_write_b16_d16_hi v25, v24 offset:14080
	v_fma_f32 v24, v28, v18, v215
	v_cvt_pk_bf16_f32 v24, v24, v24
	ds_write_b16 v35, v24 offset:14336
	v_sub_f32_e32 v24, v22, v39
	v_pk_fma_f32 v[22:23], v[40:41], s[22:23], v[22:23] op_sel_hi:[1,0,1] neg_lo:[1,0,0] neg_hi:[1,0,0]
	v_mul_f32_e32 v24, v24, v18
	v_mul_f32_e32 v22, v23, v18
	v_bfe_u32 v25, v24, 16, 1
	v_bfe_u32 v23, v22, 16, 1
	v_add3_u32 v24, v24, v25, s15
	v_add3_u32 v22, v22, v23, s15
	ds_write_b16_d16_hi v55, v24 offset:14592
	ds_write_b16_d16_hi v56, v22 offset:14848
	v_pk_fma_f32 v[22:23], v[40:41], s[22:23], v[30:31] op_sel_hi:[1,0,1] neg_lo:[1,0,0] neg_hi:[1,0,0]
	s_nop 0
	v_mul_f32_e32 v22, v23, v18
	v_bfe_u32 v23, v22, 16, 1
	v_add3_u32 v22, v22, v23, s15
	ds_write_b16_d16_hi v54, v22 offset:15104
	v_fma_f32 v22, v26, v18, v215
	v_cvt_pk_bf16_f32 v22, v22, v22
	ds_write_b16 v53, v22 offset:15360
	v_sub_f32_e32 v22, v20, v39
	v_pk_fma_f32 v[20:21], v[40:41], s[22:23], v[20:21] op_sel_hi:[1,0,1] neg_lo:[1,0,0] neg_hi:[1,0,0]
	v_mul_f32_e32 v22, v22, v18
	v_mul_f32_e32 v20, v21, v18
	v_mul_f32_e32 v18, v19, v18
	v_bfe_u32 v23, v22, 16, 1
	v_bfe_u32 v21, v20, 16, 1
	v_bfe_u32 v19, v18, 16, 1
	v_add3_u32 v22, v22, v23, s15
	v_add3_u32 v20, v20, v21, s15
	v_add3_u32 v18, v18, v19, s15
	ds_write_b16_d16_hi v51, v22 offset:15616
	ds_write_b16_d16_hi v49, v20 offset:15872
	ds_write_b16_d16_hi v45, v18 offset:16128
	v_lshrrev_b32_e32 v18, 1, v43
	v_and_b32_e32 v18, 32, v18
	v_lshl_or_b32 v132, v44, 6, v18
	v_or_b32_e32 v18, v132, v134
	v_lshl_add_u32 v131, v18, 8, 32
	v_bitop3_b32 v18, v42, v133, 1 bitop3:0x6c
	v_lshl_add_u32 v18, v18, 4, v131
	s_waitcnt lgkmcnt(0)
	s_barrier
	ds_read_b128 v[136:139], v18 offset:55296
	s_waitcnt lgkmcnt(0)
	v_mfma_f32_32x32x16_bf16 v[50:65], v[136:139], v[2:5], 0
	v_mfma_f32_32x32x16_bf16 v[34:49], v[136:139], v[6:9], 0
	v_mfma_f32_32x32x16_bf16 v[18:33], v[136:139], v[10:13], 0
	v_mfma_f32_32x32x16_bf16 v[2:17], v[136:139], v[14:17], 0
	v_bitop3_b32 v136, v135, v133, 2 bitop3:0x36
	v_lshl_add_u32 v136, v136, 4, v131
	ds_read_b128 v[136:139], v136 offset:55296
	s_waitcnt lgkmcnt(0)
	v_mfma_f32_32x32x16_bf16 v[50:65], v[136:139], v[114:117], v[50:65]
	v_bitop3_b32 v114, v135, v133, 4 bitop3:0x36
	v_lshl_add_u32 v114, v114, 4, v131
	ds_read_b128 v[114:117], v114 offset:55296
	v_mfma_f32_32x32x16_bf16 v[34:49], v[136:139], v[118:121], v[34:49]
	v_mfma_f32_32x32x16_bf16 v[18:33], v[136:139], v[122:125], v[18:33]
	s_waitcnt lgkmcnt(0)
	v_mfma_f32_32x32x16_bf16 v[34:49], v[114:117], v[102:105], v[34:49]
	v_bitop3_b32 v102, v135, v133, 6 bitop3:0x36
	v_lshl_add_u32 v102, v102, 4, v131
	ds_read_b128 v[102:105], v102 offset:55296
	v_mfma_f32_32x32x16_bf16 v[2:17], v[136:139], v[126:129], v[2:17]
	v_mfma_f32_32x32x16_bf16 v[18:33], v[114:117], v[106:109], v[18:33]
	s_waitcnt lgkmcnt(0)
	v_mfma_f32_32x32x16_bf16 v[34:49], v[102:105], v[90:93], v[34:49]
	v_bitop3_b32 v90, v135, v133, 8 bitop3:0x36
	v_lshl_add_u32 v90, v90, 4, v131
	ds_read_b128 v[90:93], v90 offset:55296
	v_mfma_f32_32x32x16_bf16 v[2:17], v[114:117], v[110:113], v[2:17]
	v_mfma_f32_32x32x16_bf16 v[18:33], v[102:105], v[94:97], v[18:33]
	v_mfma_f32_32x32x16_bf16 v[2:17], v[102:105], v[98:101], v[2:17]
	v_lshlrev_b32_e32 v104, 7, v130
	v_or_b32_e32 v102, v104, v134
	v_ashrrev_i32_e32 v103, 31, v102
	v_lshlrev_b64 v[106:107], 2, v[102:103]
	v_lshl_or_b32 v98, v135, 2, v132
	v_or_b32_e32 v100, s3, v134
	v_mov_b32_e32 v101, s5
	s_waitcnt lgkmcnt(0)
	v_mfma_f32_32x32x16_bf16 v[18:33], v[90:93], v[82:85], v[18:33]
	v_bitop3_b32 v82, v135, v133, 10 bitop3:0x36
	v_lshl_add_u32 v82, v82, 4, v131
	ds_read_b128 v[82:85], v82 offset:55296
	v_lshl_add_u64 v[108:109], s[6:7], 0, v[106:107]
	v_lshl_add_u64 v[106:107], s[92:93], 0, v[106:107]
	v_ashrrev_i32_e32 v99, 31, v98
	v_lshlrev_b64 v[98:99], 1, v[98:99]
	v_mfma_f32_32x32x16_bf16 v[2:17], v[90:93], v[86:89], v[2:17]
	s_add_i32 s3, s3, s18
	s_cmpk_gt_i32 s4, 0x7f
	s_waitcnt lgkmcnt(0)
	v_mfma_f32_32x32x16_bf16 v[18:33], v[82:85], v[74:77], v[18:33]
	v_bitop3_b32 v74, v135, v133, 12 bitop3:0x36
	v_lshl_add_u32 v74, v74, 4, v131
	ds_read_b128 v[74:77], v74 offset:55296
	v_mfma_f32_32x32x16_bf16 v[2:17], v[82:85], v[78:81], v[2:17]
	s_waitcnt lgkmcnt(0)
	v_mfma_f32_32x32x16_bf16 v[2:17], v[74:77], v[70:73], v[2:17]
	v_bitop3_b32 v70, v135, v133, 14 bitop3:0x36
	v_lshl_add_u32 v70, v70, 4, v131
	ds_read_b128 v[70:73], v70 offset:55296
	v_ashrrev_i32_e32 v133, 31, v132
	s_waitcnt lgkmcnt(0)
	v_mfma_f32_32x32x16_bf16 v[2:17], v[70:73], v[66:69], v[2:17]
	v_lshlrev_b64 v[66:67], 2, v[132:133]
	v_lshl_add_u64 v[68:69], s[10:11], 0, v[66:67]
	v_lshl_add_u64 v[66:67], s[36:37], 0, v[66:67]
	v_lshl_add_u64 v[68:69], v[68:69], 0, v[154:155]
	v_lshl_add_u64 v[70:71], v[66:67], 0, v[154:155]
	global_load_dwordx4 v[90:93], v[68:69], off
	global_load_dwordx4 v[94:97], v[70:71], off
	global_load_dwordx4 v[82:85], v[68:69], off offset:32
	global_load_dwordx4 v[86:89], v[70:71], off offset:32
	global_load_dwordx4 v[74:77], v[68:69], off offset:64
	global_load_dwordx4 v[78:81], v[70:71], off offset:64
	s_nop 0
	global_load_dwordx4 v[66:69], v[68:69], off offset:96
	s_nop 0
	global_load_dwordx4 v[70:73], v[70:71], off offset:96
	s_nop 0
	global_load_dword v150, v[108:109], off
	global_load_dword v151, v[108:109], off offset:128
	global_load_dword v152, v[108:109], off offset:256
	global_load_dword v153, v[108:109], off offset:384
	global_load_dword v164, v[106:107], off
	global_load_dword v165, v[106:107], off offset:128
	global_load_dword v166, v[106:107], off offset:256
	global_load_dword v167, v[106:107], off offset:384
	v_lshlrev_b64 v[142:143], 11, v[100:101]
	v_lshl_add_u64 v[142:143], s[62:63], 0, v[142:143]
	v_lshl_add_u64 v[142:143], v[142:143], 0, v[98:99]
	v_bfe_u32 v169, v0, 5, 1
	v_lshlrev_b32_e32 v169, 3, v169
	v_add_co_u32_e32 v142, vcc, v142, v169
	s_nop 1
	v_addc_co_u32_e32 v143, vcc, 0, v143, vcc
	v_add_co_u32_e32 v144, vcc, 0x10000, v142
	s_nop 1
	v_addc_co_u32_e32 v145, vcc, 0, v143, vcc
	v_add_co_u32_e32 v146, vcc, 0x20000, v142
	s_nop 1
	v_addc_co_u32_e32 v147, vcc, 0, v143, vcc
	v_add_co_u32_e32 v148, vcc, 0x30000, v142
	s_nop 1
	v_addc_co_u32_e32 v149, vcc, 0, v143, vcc
	s_waitcnt vmcnt(0)
	s_nop 1
	v_permlane32_swap_b32 v216, v218
	v_permlane32_swap_b32 v217, v219
	v_permlane32_swap_b32 v220, v222
	v_permlane32_swap_b32 v221, v223
	v_permlane32_swap_b32 v224, v226
	v_permlane32_swap_b32 v225, v227
	v_permlane32_swap_b32 v228, v230
	v_permlane32_swap_b32 v229, v231
	v_permlane32_swap_b32 v232, v234
	v_permlane32_swap_b32 v233, v235
	v_permlane32_swap_b32 v236, v238
	v_permlane32_swap_b32 v237, v239
	v_permlane32_swap_b32 v252, v254
	v_permlane32_swap_b32 v253, v255
	v_mul_f32_e32 v168, v94, v150
	v_fmac_f32_e32 v168, v50, v90
	v_add_f32_e32 v50, v164, v168
	v_lshlrev_b32_e32 v169, 16, v216
	v_mul_f32_e32 v50, v50, v169
	v_mul_f32_e32 v168, v95, v150
	v_fmac_f32_e32 v168, v51, v91
	v_add_f32_e32 v51, v164, v168
	v_and_b32_e32 v169, 0xffff0000, v216
	v_mul_f32_e32 v51, v51, v169
	v_mul_f32_e32 v168, v96, v150
	v_fmac_f32_e32 v168, v52, v92
	v_add_f32_e32 v52, v164, v168
	v_lshlrev_b32_e32 v169, 16, v217
	v_mul_f32_e32 v52, v52, v169
	v_mul_f32_e32 v168, v97, v150
	v_fmac_f32_e32 v168, v53, v93
	v_add_f32_e32 v53, v164, v168
	v_and_b32_e32 v169, 0xffff0000, v217
	v_mul_f32_e32 v53, v53, v169
	v_cvt_pk_bf16_f32 v50, v50, v51
	v_cvt_pk_bf16_f32 v51, v52, v53
	v_mul_f32_e32 v168, v86, v150
	v_fmac_f32_e32 v168, v54, v82
	v_add_f32_e32 v54, v164, v168
	v_lshlrev_b32_e32 v169, 16, v218
	v_mul_f32_e32 v54, v54, v169
	v_mul_f32_e32 v168, v87, v150
	v_fmac_f32_e32 v168, v55, v83
	v_add_f32_e32 v55, v164, v168
	v_and_b32_e32 v169, 0xffff0000, v218
	v_mul_f32_e32 v55, v55, v169
	v_mul_f32_e32 v168, v88, v150
	v_fmac_f32_e32 v168, v56, v84
	v_add_f32_e32 v56, v164, v168
	v_lshlrev_b32_e32 v169, 16, v219
	v_mul_f32_e32 v56, v56, v169
	v_mul_f32_e32 v168, v89, v150
	v_fmac_f32_e32 v168, v57, v85
	v_add_f32_e32 v57, v164, v168
	v_and_b32_e32 v169, 0xffff0000, v219
	v_mul_f32_e32 v57, v57, v169
	v_cvt_pk_bf16_f32 v52, v54, v55
	v_cvt_pk_bf16_f32 v53, v56, v57
	s_nop 1
	v_permlane32_swap_b32 v50, v52
	v_permlane32_swap_b32 v51, v53
	global_store_dwordx4 v[142:143], v[50:53], off offset:1536
	v_mul_f32_e32 v168, v78, v150
	v_fmac_f32_e32 v168, v58, v74
	v_add_f32_e32 v58, v164, v168
	v_lshlrev_b32_e32 v169, 16, v220
	v_mul_f32_e32 v58, v58, v169
	v_mul_f32_e32 v168, v79, v150
	v_fmac_f32_e32 v168, v59, v75
	v_add_f32_e32 v59, v164, v168
	v_and_b32_e32 v169, 0xffff0000, v220
	v_mul_f32_e32 v59, v59, v169
	v_mul_f32_e32 v168, v80, v150
	v_fmac_f32_e32 v168, v60, v76
	v_add_f32_e32 v60, v164, v168
	v_lshlrev_b32_e32 v169, 16, v221
	v_mul_f32_e32 v60, v60, v169
	v_mul_f32_e32 v168, v81, v150
	v_fmac_f32_e32 v168, v61, v77
	v_add_f32_e32 v61, v164, v168
	v_and_b32_e32 v169, 0xffff0000, v221
	v_mul_f32_e32 v61, v61, v169
	v_cvt_pk_bf16_f32 v58, v58, v59
	v_cvt_pk_bf16_f32 v59, v60, v61
	v_mul_f32_e32 v168, v70, v150
	v_fmac_f32_e32 v168, v62, v66
	v_add_f32_e32 v62, v164, v168
	v_lshlrev_b32_e32 v169, 16, v222
	v_mul_f32_e32 v62, v62, v169
	v_mul_f32_e32 v168, v71, v150
	v_fmac_f32_e32 v168, v63, v67
	v_add_f32_e32 v63, v164, v168
	v_and_b32_e32 v169, 0xffff0000, v222
	v_mul_f32_e32 v63, v63, v169
	v_mul_f32_e32 v168, v72, v150
	v_fmac_f32_e32 v168, v64, v68
	v_add_f32_e32 v64, v164, v168
	v_lshlrev_b32_e32 v169, 16, v223
	v_mul_f32_e32 v64, v64, v169
	v_mul_f32_e32 v168, v73, v150
	v_fmac_f32_e32 v168, v65, v69
	v_add_f32_e32 v65, v164, v168
	v_and_b32_e32 v169, 0xffff0000, v223
	v_mul_f32_e32 v65, v65, v169
	v_cvt_pk_bf16_f32 v60, v62, v63
	v_cvt_pk_bf16_f32 v61, v64, v65
	s_nop 1
	v_permlane32_swap_b32 v58, v60
	v_permlane32_swap_b32 v59, v61
	global_store_dwordx4 v[142:143], v[58:61], off offset:1568
	v_mul_f32_e32 v168, v94, v151
	v_fmac_f32_e32 v168, v34, v90
	v_add_f32_e32 v34, v165, v168
	v_lshlrev_b32_e32 v169, 16, v224
	v_mul_f32_e32 v34, v34, v169
	v_mul_f32_e32 v168, v95, v151
	v_fmac_f32_e32 v168, v35, v91
	v_add_f32_e32 v35, v165, v168
	v_and_b32_e32 v169, 0xffff0000, v224
	v_mul_f32_e32 v35, v35, v169
	v_mul_f32_e32 v168, v96, v151
	v_fmac_f32_e32 v168, v36, v92
	v_add_f32_e32 v36, v165, v168
	v_lshlrev_b32_e32 v169, 16, v225
	v_mul_f32_e32 v36, v36, v169
	v_mul_f32_e32 v168, v97, v151
	v_fmac_f32_e32 v168, v37, v93
	v_add_f32_e32 v37, v165, v168
	v_and_b32_e32 v169, 0xffff0000, v225
	v_mul_f32_e32 v37, v37, v169
	v_cvt_pk_bf16_f32 v34, v34, v35
	v_cvt_pk_bf16_f32 v35, v36, v37
	v_mul_f32_e32 v168, v86, v151
	v_fmac_f32_e32 v168, v38, v82
	v_add_f32_e32 v38, v165, v168
	v_lshlrev_b32_e32 v169, 16, v226
	v_mul_f32_e32 v38, v38, v169
	v_mul_f32_e32 v168, v87, v151
	v_fmac_f32_e32 v168, v39, v83
	v_add_f32_e32 v39, v165, v168
	v_and_b32_e32 v169, 0xffff0000, v226
	v_mul_f32_e32 v39, v39, v169
	v_mul_f32_e32 v168, v88, v151
	v_fmac_f32_e32 v168, v40, v84
	v_add_f32_e32 v40, v165, v168
	v_lshlrev_b32_e32 v169, 16, v227
	v_mul_f32_e32 v40, v40, v169
	v_mul_f32_e32 v168, v89, v151
	v_fmac_f32_e32 v168, v41, v85
	v_add_f32_e32 v41, v165, v168
	v_and_b32_e32 v169, 0xffff0000, v227
	v_mul_f32_e32 v41, v41, v169
	v_cvt_pk_bf16_f32 v36, v38, v39
	v_cvt_pk_bf16_f32 v37, v40, v41
	s_nop 1
	v_permlane32_swap_b32 v34, v36
	v_permlane32_swap_b32 v35, v37
	global_store_dwordx4 v[144:145], v[34:37], off offset:1536
	v_mul_f32_e32 v168, v78, v151
	v_fmac_f32_e32 v168, v42, v74
	v_add_f32_e32 v42, v165, v168
	v_lshlrev_b32_e32 v169, 16, v228
	v_mul_f32_e32 v42, v42, v169
	v_mul_f32_e32 v168, v79, v151
	v_fmac_f32_e32 v168, v43, v75
	v_add_f32_e32 v43, v165, v168
	v_and_b32_e32 v169, 0xffff0000, v228
	v_mul_f32_e32 v43, v43, v169
	v_mul_f32_e32 v168, v80, v151
	v_fmac_f32_e32 v168, v44, v76
	v_add_f32_e32 v44, v165, v168
	v_lshlrev_b32_e32 v169, 16, v229
	v_mul_f32_e32 v44, v44, v169
	v_mul_f32_e32 v168, v81, v151
	v_fmac_f32_e32 v168, v45, v77
	v_add_f32_e32 v45, v165, v168
	v_and_b32_e32 v169, 0xffff0000, v229
	v_mul_f32_e32 v45, v45, v169
	v_cvt_pk_bf16_f32 v42, v42, v43
	v_cvt_pk_bf16_f32 v43, v44, v45
	v_mul_f32_e32 v168, v70, v151
	v_fmac_f32_e32 v168, v46, v66
	v_add_f32_e32 v46, v165, v168
	v_lshlrev_b32_e32 v169, 16, v230
	v_mul_f32_e32 v46, v46, v169
	v_mul_f32_e32 v168, v71, v151
	v_fmac_f32_e32 v168, v47, v67
	v_add_f32_e32 v47, v165, v168
	v_and_b32_e32 v169, 0xffff0000, v230
	v_mul_f32_e32 v47, v47, v169
	v_mul_f32_e32 v168, v72, v151
	v_fmac_f32_e32 v168, v48, v68
	v_add_f32_e32 v48, v165, v168
	v_lshlrev_b32_e32 v169, 16, v231
	v_mul_f32_e32 v48, v48, v169
	v_mul_f32_e32 v168, v73, v151
	v_fmac_f32_e32 v168, v49, v69
	v_add_f32_e32 v49, v165, v168
	v_and_b32_e32 v169, 0xffff0000, v231
	v_mul_f32_e32 v49, v49, v169
	v_cvt_pk_bf16_f32 v44, v46, v47
	v_cvt_pk_bf16_f32 v45, v48, v49
	s_nop 1
	v_permlane32_swap_b32 v42, v44
	v_permlane32_swap_b32 v43, v45
	global_store_dwordx4 v[144:145], v[42:45], off offset:1568
	v_mul_f32_e32 v168, v94, v152
	v_fmac_f32_e32 v168, v18, v90
	v_add_f32_e32 v18, v166, v168
	v_lshlrev_b32_e32 v169, 16, v232
	v_mul_f32_e32 v18, v18, v169
	v_mul_f32_e32 v168, v95, v152
	v_fmac_f32_e32 v168, v19, v91
	v_add_f32_e32 v19, v166, v168
	v_and_b32_e32 v169, 0xffff0000, v232
	v_mul_f32_e32 v19, v19, v169
	v_mul_f32_e32 v168, v96, v152
	v_fmac_f32_e32 v168, v20, v92
	v_add_f32_e32 v20, v166, v168
	v_lshlrev_b32_e32 v169, 16, v233
	v_mul_f32_e32 v20, v20, v169
	v_mul_f32_e32 v168, v97, v152
	v_fmac_f32_e32 v168, v21, v93
	v_add_f32_e32 v21, v166, v168
	v_and_b32_e32 v169, 0xffff0000, v233
	v_mul_f32_e32 v21, v21, v169
	v_cvt_pk_bf16_f32 v18, v18, v19
	v_cvt_pk_bf16_f32 v19, v20, v21
	v_mul_f32_e32 v168, v86, v152
	v_fmac_f32_e32 v168, v22, v82
	v_add_f32_e32 v22, v166, v168
	v_lshlrev_b32_e32 v169, 16, v234
	v_mul_f32_e32 v22, v22, v169
	v_mul_f32_e32 v168, v87, v152
	v_fmac_f32_e32 v168, v23, v83
	v_add_f32_e32 v23, v166, v168
	v_and_b32_e32 v169, 0xffff0000, v234
	v_mul_f32_e32 v23, v23, v169
	v_mul_f32_e32 v168, v88, v152
	v_fmac_f32_e32 v168, v24, v84
	v_add_f32_e32 v24, v166, v168
	v_lshlrev_b32_e32 v169, 16, v235
	v_mul_f32_e32 v24, v24, v169
	v_mul_f32_e32 v168, v89, v152
	v_fmac_f32_e32 v168, v25, v85
	v_add_f32_e32 v25, v166, v168
	v_and_b32_e32 v169, 0xffff0000, v235
	v_mul_f32_e32 v25, v25, v169
	v_cvt_pk_bf16_f32 v20, v22, v23
	v_cvt_pk_bf16_f32 v21, v24, v25
	s_nop 1
	v_permlane32_swap_b32 v18, v20
	v_permlane32_swap_b32 v19, v21
	global_store_dwordx4 v[146:147], v[18:21], off offset:1536
	v_mul_f32_e32 v168, v78, v152
	v_fmac_f32_e32 v168, v26, v74
	v_add_f32_e32 v26, v166, v168
	v_lshlrev_b32_e32 v169, 16, v236
	v_mul_f32_e32 v26, v26, v169
	v_mul_f32_e32 v168, v79, v152
	v_fmac_f32_e32 v168, v27, v75
	v_add_f32_e32 v27, v166, v168
	v_and_b32_e32 v169, 0xffff0000, v236
	v_mul_f32_e32 v27, v27, v169
	v_mul_f32_e32 v168, v80, v152
	v_fmac_f32_e32 v168, v28, v76
	v_add_f32_e32 v28, v166, v168
	v_lshlrev_b32_e32 v169, 16, v237
	v_mul_f32_e32 v28, v28, v169
	v_mul_f32_e32 v168, v81, v152
	v_fmac_f32_e32 v168, v29, v77
	v_add_f32_e32 v29, v166, v168
	v_and_b32_e32 v169, 0xffff0000, v237
	v_mul_f32_e32 v29, v29, v169
	v_cvt_pk_bf16_f32 v26, v26, v27
	v_cvt_pk_bf16_f32 v27, v28, v29
	v_mul_f32_e32 v168, v70, v152
	v_fmac_f32_e32 v168, v30, v66
	v_add_f32_e32 v30, v166, v168
	v_lshlrev_b32_e32 v169, 16, v238
	v_mul_f32_e32 v30, v30, v169
	v_mul_f32_e32 v168, v71, v152
	v_fmac_f32_e32 v168, v31, v67
	v_add_f32_e32 v31, v166, v168
	v_and_b32_e32 v169, 0xffff0000, v238
	v_mul_f32_e32 v31, v31, v169
	v_mul_f32_e32 v168, v72, v152
	v_fmac_f32_e32 v168, v32, v68
	v_add_f32_e32 v32, v166, v168
	v_lshlrev_b32_e32 v169, 16, v239
	v_mul_f32_e32 v32, v32, v169
	v_mul_f32_e32 v168, v73, v152
	v_fmac_f32_e32 v168, v33, v69
	v_add_f32_e32 v33, v166, v168
	v_and_b32_e32 v169, 0xffff0000, v239
	v_mul_f32_e32 v33, v33, v169
	v_cvt_pk_bf16_f32 v28, v30, v31
	v_cvt_pk_bf16_f32 v29, v32, v33
	s_nop 1
	v_permlane32_swap_b32 v26, v28
	v_permlane32_swap_b32 v27, v29
	global_store_dwordx4 v[146:147], v[26:29], off offset:1568
	v_mul_f32_e32 v168, v94, v153
	v_fmac_f32_e32 v168, v2, v90
	v_add_f32_e32 v2, v167, v168
	v_lshlrev_b32_e32 v169, 16, v252
	v_mul_f32_e32 v2, v2, v169
	v_mul_f32_e32 v168, v95, v153
	v_fmac_f32_e32 v168, v3, v91
	v_add_f32_e32 v3, v167, v168
	v_and_b32_e32 v169, 0xffff0000, v252
	v_mul_f32_e32 v3, v3, v169
	v_mul_f32_e32 v168, v96, v153
	v_fmac_f32_e32 v168, v4, v92
	v_add_f32_e32 v4, v167, v168
	v_lshlrev_b32_e32 v169, 16, v253
	v_mul_f32_e32 v4, v4, v169
	v_mul_f32_e32 v168, v97, v153
	v_fmac_f32_e32 v168, v5, v93
	v_add_f32_e32 v5, v167, v168
	v_and_b32_e32 v169, 0xffff0000, v253
	v_mul_f32_e32 v5, v5, v169
	v_cvt_pk_bf16_f32 v2, v2, v3
	v_cvt_pk_bf16_f32 v3, v4, v5
	v_mul_f32_e32 v168, v86, v153
	v_fmac_f32_e32 v168, v6, v82
	v_add_f32_e32 v6, v167, v168
	v_lshlrev_b32_e32 v169, 16, v254
	v_mul_f32_e32 v6, v6, v169
	v_mul_f32_e32 v168, v87, v153
	v_fmac_f32_e32 v168, v7, v83
	v_add_f32_e32 v7, v167, v168
	v_and_b32_e32 v169, 0xffff0000, v254
	v_mul_f32_e32 v7, v7, v169
	v_mul_f32_e32 v168, v88, v153
	v_fmac_f32_e32 v168, v8, v84
	v_add_f32_e32 v8, v167, v168
	v_lshlrev_b32_e32 v169, 16, v255
	v_mul_f32_e32 v8, v8, v169
	v_mul_f32_e32 v168, v89, v153
	v_fmac_f32_e32 v168, v9, v85
	v_add_f32_e32 v9, v167, v168
	v_and_b32_e32 v169, 0xffff0000, v255
	v_mul_f32_e32 v9, v9, v169
	v_cvt_pk_bf16_f32 v4, v6, v7
	v_cvt_pk_bf16_f32 v5, v8, v9
	s_nop 1
	v_permlane32_swap_b32 v2, v4
	v_permlane32_swap_b32 v3, v5
	global_store_dwordx4 v[148:149], v[2:5], off offset:1536
	v_mul_f32_e32 v168, v78, v153
	v_fmac_f32_e32 v168, v10, v74
	v_add_f32_e32 v10, v167, v168
	v_lshlrev_b32_e32 v169, 16, v240
	v_mul_f32_e32 v10, v10, v169
	v_mul_f32_e32 v168, v79, v153
	v_fmac_f32_e32 v168, v11, v75
	v_add_f32_e32 v11, v167, v168
	v_and_b32_e32 v169, 0xffff0000, v240
	v_mul_f32_e32 v11, v11, v169
	v_mul_f32_e32 v168, v80, v153
	v_fmac_f32_e32 v168, v12, v76
	v_add_f32_e32 v12, v167, v168
	v_lshlrev_b32_e32 v169, 16, v241
	v_mul_f32_e32 v12, v12, v169
	v_mul_f32_e32 v168, v81, v153
	v_fmac_f32_e32 v168, v13, v77
	v_add_f32_e32 v13, v167, v168
	v_and_b32_e32 v169, 0xffff0000, v241
	v_mul_f32_e32 v13, v13, v169
	v_cvt_pk_bf16_f32 v10, v10, v11
	v_cvt_pk_bf16_f32 v11, v12, v13
	v_mul_f32_e32 v168, v70, v153
	v_fmac_f32_e32 v168, v14, v66
	v_add_f32_e32 v14, v167, v168
	v_lshlrev_b32_e32 v169, 16, v246
	v_mul_f32_e32 v14, v14, v169
	v_mul_f32_e32 v168, v71, v153
	v_fmac_f32_e32 v168, v15, v67
	v_add_f32_e32 v15, v167, v168
	v_and_b32_e32 v169, 0xffff0000, v246
	v_mul_f32_e32 v15, v15, v169
	v_mul_f32_e32 v168, v72, v153
	v_fmac_f32_e32 v168, v16, v68
	v_add_f32_e32 v16, v167, v168
	v_lshlrev_b32_e32 v169, 16, v247
	v_mul_f32_e32 v16, v16, v169
	v_mul_f32_e32 v168, v73, v153
	v_fmac_f32_e32 v168, v17, v69
	v_add_f32_e32 v17, v167, v168
	v_and_b32_e32 v169, 0xffff0000, v247
	v_mul_f32_e32 v17, v17, v169
	v_cvt_pk_bf16_f32 v12, v14, v15
	v_cvt_pk_bf16_f32 v13, v16, v17
	s_nop 1
	v_permlane32_swap_b32 v10, v12
	v_permlane32_swap_b32 v11, v13
	global_store_dwordx4 v[148:149], v[10:13], off offset:1568
	s_barrier
	s_cbranch_scc0 .LBB0_849
